# GEMM k-loop (phases 1 and 5): last three LDS-DMA stage loads of each k-tile interleaved with the first MFMA group instead of one burst behind the barrier
# speedup vs baseline: 1.0296x; 1.0063x over previous
; template <class Epi>
; DI void gemm_phase(const u16* __restrict__ A, const u16* __restrict__ B, int mtiles, int ntiles, char* lds, const Epi& epi) {
;     ...
;     for (;;) {
;         int tid = threadIdx.x; asm volatile("" : "+v"(tid));
;         const int lane = tid & 63, wave = __builtin_amdgcn_readfirstlane(tid >> 6); const int wn = wave >> 1, wm = wave & 1; const int r = lane & 31, h = lane >> 5;
;         f32x16 acc[2][2];
; #pragma unroll
;         for (int a = 0; a < 2; ++a)
; #pragma unroll
;             for (int b = 0; b < 2; ++b)
; #pragma unroll
;                 for (int e = 0; e < 16; ++e) acc[a][b][e] = 0.f;
;         unsigned soff[4];
; #pragma unroll
;         for (int i = 0; i < 4; ++i) { const int row = 8 * (i * 4 + wave) + (lane >> 3); const int ch = (lane & 7) ^ ((row >> 1) & 7); soff[i] = (unsigned)(row * 1024 + ch * 8); }
;         const u16* ga = A + (size_t)m0 * 1024; const u16* gb = B + (size_t)n0 * 1024;
;         __syncthreads();
;         for (int kt = 0; kt < 16; ++kt) {
;             if (kt + 1 < 16) GSTAGE((kt + 1) & 1, kt + 1, ga, gb);
;             const char* sa = lds + (kt & 1) * 32768; const char* sb = sa + 16384;
; #pragma unroll
;             for (int ks = 0; ks < 4; ++ks) {
;                 bf16x8 fw[2], fx[2];
; #pragma unroll
;                 for (int ct = 0; ct < 2; ++ct) fw[ct] = *(const bf16x8*)(sb + swz(wn * 64 + ct * 32 + r, 2 * ks + h));
; #pragma unroll
;                 for (int tt = 0; tt < 2; ++tt) fx[tt] = *(const bf16x8*)(sa + swz(wm * 64 + tt * 32 + r, 2 * ks + h));
.LBB0_97:
	v_mov_b32_e32 v18, v0
	s_ashr_i32 s83, s82, 31
	v_readfirstlane_b32 s1, v18
	s_ashr_i32 s7, s1, 6
	s_ashr_i32 s4, s1, 7
	s_and_b32 s6, s7, 1
	v_bfe_u32 v2, v18, 3, 3
	s_lshl_b64 s[38:39], s[82:83], 11
	v_lshl_or_b32 v2, s7, 3, v2
	s_add_u32 s38, s54, s38
	v_lshrrev_b32_e32 v3, 1, v2
	s_addc_u32 s39, s55, s39
	s_ashr_i32 s1, s0, 31
	v_xor_b32_e32 v3, v3, v18
	s_lshl_b64 s[50:51], s[0:1], 11
	v_readlane_b32 s1, v236, 9
	v_lshlrev_b32_e32 v2, 10, v2
	v_lshlrev_b32_e32 v3, 3, v3
	s_add_u32 s50, s1, s50
	v_readlane_b32 s1, v236, 11
	v_and_or_b32 v74, v3, 56, v2
	s_addc_u32 s51, s1, s51
	s_lshl_b32 s1, s7, 10
	v_lshlrev_b64 v[66:67], 1, v[74:75]
	s_add_i32 s1, s1, 0
	v_add_u32_e32 v2, 0x8000, v74
	v_bfe_u32 v93, v18, 5, 1
	v_lshrrev_b32_e32 v8, 1, v18
	v_mov_b32_e32 v3, v75
	v_lshl_add_u64 v[76:77], s[38:39], 0, v[66:67]
	s_add_i32 s86, s1, 0x8000
	v_bitop3_b32 v10, v93, v8, 7 bitop3:0x78
	v_lshl_add_u64 v[8:9], v[76:77], 0, s[8:9]
	s_mov_b32 m0, s86
	v_lshl_add_u64 v[78:79], s[50:51], 0, v[66:67]
	s_add_i32 s87, s1, 0xc000
	v_lshlrev_b64 v[68:69], 1, v[2:3]
	v_add_u32_e32 v4, 0x10000, v74
	s_waitcnt vmcnt(0) lgkmcnt(0)
	s_barrier
	v_mov_b32_e32 v5, v75
	global_load_lds_dwordx4 v[8:9], off
	v_lshl_add_u64 v[8:9], v[78:79], 0, s[8:9]
	s_mov_b32 m0, s87
	v_lshl_add_u64 v[80:81], s[38:39], 0, v[68:69]
	s_add_i32 s88, s1, 0x9000
	global_load_lds_dwordx4 v[8:9], off
	v_lshl_add_u64 v[2:3], v[80:81], 0, s[8:9]
	s_mov_b32 m0, s88
	v_lshl_add_u64 v[82:83], s[50:51], 0, v[68:69]
	s_add_i32 s89, s1, 0xd000
	v_lshlrev_b64 v[70:71], 1, v[4:5]
	v_add_u32_e32 v6, 0x18000, v74
	v_mov_b32_e32 v7, v75
	global_load_lds_dwordx4 v[2:3], off
	v_lshl_add_u64 v[2:3], v[82:83], 0, s[8:9]
	s_mov_b32 m0, s89
	v_lshl_add_u64 v[84:85], s[38:39], 0, v[70:71]
	s_add_i32 s91, s1, 0xa000
	global_load_lds_dwordx4 v[2:3], off
	v_lshl_add_u64 v[2:3], v[84:85], 0, s[8:9]
	s_mov_b32 m0, s91
	v_lshl_add_u64 v[86:87], s[50:51], 0, v[70:71]
	s_add_i32 s92, s1, 0xe000
	v_lshlrev_b64 v[72:73], 1, v[6:7]
	global_load_lds_dwordx4 v[2:3], off
	v_lshl_add_u64 v[2:3], v[86:87], 0, s[8:9]
	s_mov_b32 m0, s92
	v_lshl_add_u64 v[88:89], s[38:39], 0, v[72:73]
	s_add_i32 s93, s1, 0xb000
	v_and_b32_e32 v94, 31, v18
	global_load_lds_dwordx4 v[2:3], off
	v_lshl_add_u64 v[2:3], v[88:89], 0, s[8:9]
	s_mov_b32 m0, s93
	v_lshl_add_u64 v[90:91], s[50:51], 0, v[72:73]
	s_add_i32 s94, s1, 0xf000
	s_lshl_b32 s7, s4, 13
	v_lshlrev_b32_e32 v116, 7, v94
	global_load_lds_dwordx4 v[2:3], off
	v_lshl_add_u64 v[2:3], v[90:91], 0, s[8:9]
	s_mov_b32 m0, s94
	v_lshl_add_u32 v6, v10, 4, 0
	global_load_lds_dwordx4 v[2:3], off
	v_add3_u32 v74, v6, s7, v116
	ds_read_b128 v[2:5], v74 offset:16384
	s_lshl_b32 s38, s6, 13
	v_add3_u32 v96, v6, s38, v116
	v_bfe_u32 v117, v18, 1, 3
	ds_read_b128 v[6:9], v96
	ds_read_b128 v[10:13], v96 offset:4096
	ds_read_b128 v[14:17], v74 offset:20480
	v_bitop3_b32 v18, v93, v117, 2 bitop3:0x36
	v_lshl_add_u32 v18, v18, 4, 0
	v_add3_u32 v95, v18, s7, v116
	ds_read_b128 v[50:53], v95 offset:16384
	s_waitcnt lgkmcnt(0)
	v_mfma_f32_32x32x16_bf16 v[34:49], v[2:5], v[6:9], 0
	v_add3_u32 v97, v18, s38, v116
	ds_read_b128 v[98:101], v97
	ds_read_b128 v[102:105], v97 offset:4096
	ds_read_b128 v[106:109], v95 offset:20480
	s_mov_b32 m0, s1
	s_add_i32 s39, s1, 0x5000
	s_add_i32 s50, s1, 0x2000
	s_add_i32 s51, s1, 0x6000
	s_add_i32 s83, s1, 0x3000
	v_mfma_f32_32x32x16_bf16 v[18:33], v[2:5], v[10:13], 0
	s_add_i32 s90, s1, 0x7000
	s_add_i32 s33, s33, s95
	s_waitcnt lgkmcnt(0)
	v_mfma_f32_32x32x16_bf16 v[34:49], v[50:53], v[98:101], v[34:49]
	v_mfma_f32_32x32x16_bf16 v[18:33], v[50:53], v[102:105], v[18:33]
	v_mfma_f32_32x32x16_bf16 v[50:65], v[14:17], v[6:9], 0
	v_mfma_f32_32x32x16_bf16 v[2:17], v[14:17], v[10:13], 0
	v_mfma_f32_32x32x16_bf16 v[50:65], v[106:109], v[98:101], v[50:65]
	v_bitop3_b32 v98, v93, v117, 4 bitop3:0x36
	v_lshl_add_u32 v99, v98, 4, 0
	v_add3_u32 v98, v99, s7, v116
	v_add3_u32 v99, v99, s38, v116
	v_mfma_f32_32x32x16_bf16 v[2:17], v[106:109], v[102:105], v[2:17]
	ds_read_b128 v[100:103], v98 offset:16384
	ds_read_b128 v[104:107], v99
	ds_read_b128 v[108:111], v99 offset:4096
	ds_read_b128 v[112:115], v98 offset:20480
	s_waitcnt lgkmcnt(0)
	v_mfma_f32_32x32x16_bf16 v[34:49], v[100:103], v[104:107], v[34:49]
	v_mfma_f32_32x32x16_bf16 v[18:33], v[100:103], v[108:111], v[18:33]
	v_bitop3_b32 v100, v93, v117, 6 bitop3:0x36
	v_lshl_add_u32 v101, v100, 4, 0
	v_add3_u32 v100, v101, s7, v116
	v_add3_u32 v101, v101, s38, v116
	s_add_i32 s7, s1, 0x4000
	s_add_i32 s38, s1, 0x1000
	s_cmpk_gt_i32 s33, 0x1103
	v_mfma_f32_32x32x16_bf16 v[50:65], v[112:115], v[104:107], v[50:65]
	v_mfma_f32_32x32x16_bf16 v[2:17], v[112:115], v[108:111], v[2:17]
	ds_read_b128 v[238:241], v100 offset:16384
	ds_read_b128 v[242:245], v101
	ds_read_b128 v[246:249], v101 offset:4096
	ds_read_b128 v[250:253], v100 offset:20480
	s_waitcnt vmcnt(0) lgkmcnt(0)
	s_barrier
; template <class Epi>
; DI void gemm_phase(const u16* __restrict__ A, const u16* __restrict__ B, int mtiles, int ntiles, char* lds, const Epi& epi) {
;     ...
;         for (int kt = 0; kt < 16; ++kt) {
;             if (kt + 1 < 16) GSTAGE((kt + 1) & 1, kt + 1, ga, gb);
;             const char* sa = lds + (kt & 1) * 32768; const char* sb = sa + 16384;
; #pragma unroll
;             for (int ks = 0; ks < 4; ++ks) {
;                 bf16x8 fw[2], fx[2];
; #pragma unroll
;                 for (int ct = 0; ct < 2; ++ct) fw[ct] = *(const bf16x8*)(sb + swz(wn * 64 + ct * 32 + r, 2 * ks + h));
; #pragma unroll
;                 for (int tt = 0; tt < 2; ++tt) fx[tt] = *(const bf16x8*)(sa + swz(wm * 64 + tt * 32 + r, 2 * ks + h));
; #pragma unroll
;                 for (int ct = 0; ct < 2; ++ct)
; #pragma unroll
;                     for (int tt = 0; tt < 2; ++tt) acc[ct][tt] = __builtin_amdgcn_mfma_f32_32x32x16_bf16(fw[ct], fx[tt], acc[ct][tt], 0, 0, 0);
;             }
;             __syncthreads();
;         }
	ds_read_b128 v[102:105], v74 offset:49152
	ds_read_b128 v[106:109], v96 offset:32768
	ds_read_b128 v[110:113], v96 offset:36864
	ds_read_b128 v[114:117], v74 offset:53248
	v_mfma_f32_32x32x16_bf16 v[34:49], v[238:241], v[242:245], v[34:49]
	v_mfma_f32_32x32x16_bf16 v[18:33], v[238:241], v[246:249], v[18:33]
	v_lshl_add_u64 v[254:255], v[76:77], 0, s[10:11]
	global_load_lds_dwordx4 v[254:255], off
	v_lshl_add_u64 v[254:255], v[78:79], 0, s[10:11]
	s_mov_b32 m0, s7
	s_nop 0
	global_load_lds_dwordx4 v[254:255], off
	v_lshl_add_u64 v[254:255], v[80:81], 0, s[10:11]
	s_mov_b32 m0, s38
	v_mfma_f32_32x32x16_bf16 v[50:65], v[250:253], v[242:245], v[50:65]
	global_load_lds_dwordx4 v[254:255], off
	v_lshl_add_u64 v[254:255], v[82:83], 0, s[10:11]
	s_mov_b32 m0, s39
	s_nop 0
	global_load_lds_dwordx4 v[254:255], off
	v_lshl_add_u64 v[254:255], v[84:85], 0, s[10:11]
	s_mov_b32 m0, s50
	v_mfma_f32_32x32x16_bf16 v[2:17], v[250:253], v[246:249], v[2:17]
	global_load_lds_dwordx4 v[254:255], off
	s_waitcnt lgkmcnt(0)
	ds_read_b128 v[238:241], v95 offset:49152
	ds_read_b128 v[242:245], v97 offset:32768
	ds_read_b128 v[246:249], v97 offset:36864
	ds_read_b128 v[250:253], v95 offset:53248
	v_mfma_f32_32x32x16_bf16 v[34:49], v[102:105], v[106:109], v[34:49]
	v_lshl_add_u64 v[254:255], v[86:87], 0, s[10:11]
	s_mov_b32 m0, s51
	s_nop 0
	global_load_lds_dwordx4 v[254:255], off
	v_mfma_f32_32x32x16_bf16 v[18:33], v[102:105], v[110:113], v[18:33]
	v_lshl_add_u64 v[254:255], v[88:89], 0, s[10:11]
	s_mov_b32 m0, s83
	s_nop 0
	global_load_lds_dwordx4 v[254:255], off
	v_mfma_f32_32x32x16_bf16 v[50:65], v[114:117], v[106:109], v[50:65]
	v_lshl_add_u64 v[254:255], v[90:91], 0, s[10:11]
	s_mov_b32 m0, s90
	s_nop 0
	global_load_lds_dwordx4 v[254:255], off
	v_mfma_f32_32x32x16_bf16 v[2:17], v[114:117], v[110:113], v[2:17]
	s_mov_b32 m0, s86
	s_waitcnt lgkmcnt(0)
	ds_read_b128 v[102:105], v98 offset:49152
	ds_read_b128 v[106:109], v99 offset:32768
	ds_read_b128 v[110:113], v99 offset:36864
	ds_read_b128 v[114:117], v98 offset:53248
	v_mfma_f32_32x32x16_bf16 v[34:49], v[238:241], v[242:245], v[34:49]
	v_mfma_f32_32x32x16_bf16 v[18:33], v[238:241], v[246:249], v[18:33]
	v_mfma_f32_32x32x16_bf16 v[50:65], v[250:253], v[242:245], v[50:65]
	v_mfma_f32_32x32x16_bf16 v[2:17], v[250:253], v[246:249], v[2:17]
	s_waitcnt lgkmcnt(0)
	ds_read_b128 v[238:241], v100 offset:49152
	ds_read_b128 v[242:245], v101 offset:32768
	ds_read_b128 v[246:249], v101 offset:36864
	ds_read_b128 v[250:253], v100 offset:53248
	v_mfma_f32_32x32x16_bf16 v[34:49], v[102:105], v[106:109], v[34:49]
	v_mfma_f32_32x32x16_bf16 v[18:33], v[102:105], v[110:113], v[18:33]
	v_mfma_f32_32x32x16_bf16 v[50:65], v[114:117], v[106:109], v[50:65]
	v_mfma_f32_32x32x16_bf16 v[2:17], v[114:117], v[110:113], v[2:17]
	s_waitcnt vmcnt(0) lgkmcnt(0)
	s_barrier
	ds_read_b128 v[102:105], v74 offset:16384
	ds_read_b128 v[106:109], v96
	ds_read_b128 v[110:113], v96 offset:4096
	ds_read_b128 v[114:117], v74 offset:20480
	v_mfma_f32_32x32x16_bf16 v[34:49], v[238:241], v[242:245], v[34:49]
	v_mfma_f32_32x32x16_bf16 v[18:33], v[238:241], v[246:249], v[18:33]
	v_lshl_add_u64 v[254:255], v[76:77], 0, s[12:13]
	global_load_lds_dwordx4 v[254:255], off
	v_lshl_add_u64 v[254:255], v[78:79], 0, s[12:13]
	s_mov_b32 m0, s87
	s_nop 0
	global_load_lds_dwordx4 v[254:255], off
	v_lshl_add_u64 v[254:255], v[80:81], 0, s[12:13]
	s_mov_b32 m0, s88
	v_mfma_f32_32x32x16_bf16 v[50:65], v[250:253], v[242:245], v[50:65]
	global_load_lds_dwordx4 v[254:255], off
	v_lshl_add_u64 v[254:255], v[82:83], 0, s[12:13]
	s_mov_b32 m0, s89
	s_nop 0
	global_load_lds_dwordx4 v[254:255], off
	v_lshl_add_u64 v[254:255], v[84:85], 0, s[12:13]
	s_mov_b32 m0, s91
	v_mfma_f32_32x32x16_bf16 v[2:17], v[250:253], v[246:249], v[2:17]
	global_load_lds_dwordx4 v[254:255], off
	s_waitcnt lgkmcnt(0)
	ds_read_b128 v[238:241], v95 offset:16384
	ds_read_b128 v[242:245], v97
	ds_read_b128 v[246:249], v97 offset:4096
	ds_read_b128 v[250:253], v95 offset:20480
	v_mfma_f32_32x32x16_bf16 v[34:49], v[102:105], v[106:109], v[34:49]
	v_lshl_add_u64 v[254:255], v[86:87], 0, s[12:13]
	s_mov_b32 m0, s92
	s_nop 0
	global_load_lds_dwordx4 v[254:255], off
	v_mfma_f32_32x32x16_bf16 v[18:33], v[102:105], v[110:113], v[18:33]
	v_lshl_add_u64 v[254:255], v[88:89], 0, s[12:13]
	s_mov_b32 m0, s93
	s_nop 0
	global_load_lds_dwordx4 v[254:255], off
	v_mfma_f32_32x32x16_bf16 v[50:65], v[114:117], v[106:109], v[50:65]
	v_lshl_add_u64 v[254:255], v[90:91], 0, s[12:13]
	s_mov_b32 m0, s94
	s_nop 0
	global_load_lds_dwordx4 v[254:255], off
	v_mfma_f32_32x32x16_bf16 v[2:17], v[114:117], v[110:113], v[2:17]
	s_mov_b32 m0, s1
	s_waitcnt lgkmcnt(0)
	ds_read_b128 v[102:105], v98 offset:16384
	ds_read_b128 v[106:109], v99
	ds_read_b128 v[110:113], v99 offset:4096
	ds_read_b128 v[114:117], v98 offset:20480
	v_mfma_f32_32x32x16_bf16 v[34:49], v[238:241], v[242:245], v[34:49]
	v_mfma_f32_32x32x16_bf16 v[18:33], v[238:241], v[246:249], v[18:33]
	v_mfma_f32_32x32x16_bf16 v[50:65], v[250:253], v[242:245], v[50:65]
	v_mfma_f32_32x32x16_bf16 v[2:17], v[250:253], v[246:249], v[2:17]
	s_waitcnt lgkmcnt(0)
	ds_read_b128 v[238:241], v100 offset:16384
	ds_read_b128 v[242:245], v101
	ds_read_b128 v[246:249], v101 offset:4096
	ds_read_b128 v[250:253], v100 offset:20480
	v_mfma_f32_32x32x16_bf16 v[34:49], v[102:105], v[106:109], v[34:49]
	v_mfma_f32_32x32x16_bf16 v[18:33], v[102:105], v[110:113], v[18:33]
	v_mfma_f32_32x32x16_bf16 v[50:65], v[114:117], v[106:109], v[50:65]
	v_mfma_f32_32x32x16_bf16 v[2:17], v[114:117], v[110:113], v[2:17]
	s_waitcnt vmcnt(0) lgkmcnt(0)
	s_barrier
; template <class Epi>
; DI void gemm_phase(const u16* __restrict__ A, const u16* __restrict__ B, int mtiles, int ntiles, char* lds, const Epi& epi) {
;     ...
;         for (int kt = 0; kt < 16; ++kt) {
;             if (kt + 1 < 16) GSTAGE((kt + 1) & 1, kt + 1, ga, gb);
;             const char* sa = lds + (kt & 1) * 32768; const char* sb = sa + 16384;
; #pragma unroll
;             for (int ks = 0; ks < 4; ++ks) {
;                 bf16x8 fw[2], fx[2];
; #pragma unroll
;                 for (int ct = 0; ct < 2; ++ct) fw[ct] = *(const bf16x8*)(sb + swz(wn * 64 + ct * 32 + r, 2 * ks + h));
; #pragma unroll
;                 for (int tt = 0; tt < 2; ++tt) fx[tt] = *(const bf16x8*)(sa + swz(wm * 64 + tt * 32 + r, 2 * ks + h));
; #pragma unroll
;                 for (int ct = 0; ct < 2; ++ct)
; #pragma unroll
;                     for (int tt = 0; tt < 2; ++tt) acc[ct][tt] = __builtin_amdgcn_mfma_f32_32x32x16_bf16(fw[ct], fx[tt], acc[ct][tt], 0, 0, 0);
;             }
;             __syncthreads();
;         }
	ds_read_b128 v[102:105], v74 offset:49152
	ds_read_b128 v[106:109], v96 offset:32768
	ds_read_b128 v[110:113], v96 offset:36864
	ds_read_b128 v[114:117], v74 offset:53248
	v_mfma_f32_32x32x16_bf16 v[34:49], v[238:241], v[242:245], v[34:49]
	v_mfma_f32_32x32x16_bf16 v[18:33], v[238:241], v[246:249], v[18:33]
	v_lshl_add_u64 v[254:255], v[76:77], 0, s[14:15]
	global_load_lds_dwordx4 v[254:255], off
	v_lshl_add_u64 v[254:255], v[78:79], 0, s[14:15]
	s_mov_b32 m0, s7
	s_nop 0
	global_load_lds_dwordx4 v[254:255], off
	v_lshl_add_u64 v[254:255], v[80:81], 0, s[14:15]
	s_mov_b32 m0, s38
	v_mfma_f32_32x32x16_bf16 v[50:65], v[250:253], v[242:245], v[50:65]
	global_load_lds_dwordx4 v[254:255], off
	v_lshl_add_u64 v[254:255], v[82:83], 0, s[14:15]
	s_mov_b32 m0, s39
	s_nop 0
	global_load_lds_dwordx4 v[254:255], off
	v_lshl_add_u64 v[254:255], v[84:85], 0, s[14:15]
	s_mov_b32 m0, s50
	v_mfma_f32_32x32x16_bf16 v[2:17], v[250:253], v[246:249], v[2:17]
	global_load_lds_dwordx4 v[254:255], off
	s_waitcnt lgkmcnt(0)
	ds_read_b128 v[238:241], v95 offset:49152
	ds_read_b128 v[242:245], v97 offset:32768
	ds_read_b128 v[246:249], v97 offset:36864
	ds_read_b128 v[250:253], v95 offset:53248
	v_mfma_f32_32x32x16_bf16 v[34:49], v[102:105], v[106:109], v[34:49]
	v_lshl_add_u64 v[254:255], v[86:87], 0, s[14:15]
	s_mov_b32 m0, s51
	s_nop 0
	global_load_lds_dwordx4 v[254:255], off
	v_mfma_f32_32x32x16_bf16 v[18:33], v[102:105], v[110:113], v[18:33]
	v_lshl_add_u64 v[254:255], v[88:89], 0, s[14:15]
	s_mov_b32 m0, s83
	s_nop 0
	global_load_lds_dwordx4 v[254:255], off
	v_mfma_f32_32x32x16_bf16 v[50:65], v[114:117], v[106:109], v[50:65]
	v_lshl_add_u64 v[254:255], v[90:91], 0, s[14:15]
	s_mov_b32 m0, s90
	s_nop 0
	global_load_lds_dwordx4 v[254:255], off
	v_mfma_f32_32x32x16_bf16 v[2:17], v[114:117], v[110:113], v[2:17]
	s_mov_b32 m0, s86
	s_waitcnt lgkmcnt(0)
	ds_read_b128 v[102:105], v98 offset:49152
	ds_read_b128 v[106:109], v99 offset:32768
	ds_read_b128 v[110:113], v99 offset:36864
	ds_read_b128 v[114:117], v98 offset:53248
	v_mfma_f32_32x32x16_bf16 v[34:49], v[238:241], v[242:245], v[34:49]
	v_mfma_f32_32x32x16_bf16 v[18:33], v[238:241], v[246:249], v[18:33]
	v_mfma_f32_32x32x16_bf16 v[50:65], v[250:253], v[242:245], v[50:65]
	v_mfma_f32_32x32x16_bf16 v[2:17], v[250:253], v[246:249], v[2:17]
	s_waitcnt lgkmcnt(0)
	ds_read_b128 v[238:241], v100 offset:49152
	ds_read_b128 v[242:245], v101 offset:32768
	ds_read_b128 v[246:249], v101 offset:36864
	ds_read_b128 v[250:253], v100 offset:53248
	v_mfma_f32_32x32x16_bf16 v[34:49], v[102:105], v[106:109], v[34:49]
	v_mfma_f32_32x32x16_bf16 v[18:33], v[102:105], v[110:113], v[18:33]
	v_mfma_f32_32x32x16_bf16 v[50:65], v[114:117], v[106:109], v[50:65]
	v_mfma_f32_32x32x16_bf16 v[2:17], v[114:117], v[110:113], v[2:17]
	s_waitcnt vmcnt(0) lgkmcnt(0)
	s_barrier
	ds_read_b128 v[102:105], v74 offset:16384
	ds_read_b128 v[106:109], v96
	ds_read_b128 v[110:113], v96 offset:4096
	ds_read_b128 v[114:117], v74 offset:20480
	v_mfma_f32_32x32x16_bf16 v[34:49], v[238:241], v[242:245], v[34:49]
	v_mfma_f32_32x32x16_bf16 v[18:33], v[238:241], v[246:249], v[18:33]
	v_lshl_add_u64 v[254:255], v[76:77], 0, s[16:17]
	global_load_lds_dwordx4 v[254:255], off
	v_lshl_add_u64 v[254:255], v[78:79], 0, s[16:17]
	s_mov_b32 m0, s87
	s_nop 0
	global_load_lds_dwordx4 v[254:255], off
	v_lshl_add_u64 v[254:255], v[80:81], 0, s[16:17]
	s_mov_b32 m0, s88
	v_mfma_f32_32x32x16_bf16 v[50:65], v[250:253], v[242:245], v[50:65]
	global_load_lds_dwordx4 v[254:255], off
	v_lshl_add_u64 v[254:255], v[82:83], 0, s[16:17]
	s_mov_b32 m0, s89
	s_nop 0
	global_load_lds_dwordx4 v[254:255], off
	v_lshl_add_u64 v[254:255], v[84:85], 0, s[16:17]
	s_mov_b32 m0, s91
	v_mfma_f32_32x32x16_bf16 v[2:17], v[250:253], v[246:249], v[2:17]
	global_load_lds_dwordx4 v[254:255], off
	s_waitcnt lgkmcnt(0)
	ds_read_b128 v[238:241], v95 offset:16384
	ds_read_b128 v[242:245], v97
	ds_read_b128 v[246:249], v97 offset:4096
	ds_read_b128 v[250:253], v95 offset:20480
	v_mfma_f32_32x32x16_bf16 v[34:49], v[102:105], v[106:109], v[34:49]
	v_lshl_add_u64 v[254:255], v[86:87], 0, s[16:17]
	s_mov_b32 m0, s92
	s_nop 0
	global_load_lds_dwordx4 v[254:255], off
	v_mfma_f32_32x32x16_bf16 v[18:33], v[102:105], v[110:113], v[18:33]
	v_lshl_add_u64 v[254:255], v[88:89], 0, s[16:17]
	s_mov_b32 m0, s93
	s_nop 0
	global_load_lds_dwordx4 v[254:255], off
	v_mfma_f32_32x32x16_bf16 v[50:65], v[114:117], v[106:109], v[50:65]
	v_lshl_add_u64 v[254:255], v[90:91], 0, s[16:17]
	s_mov_b32 m0, s94
	s_nop 0
	global_load_lds_dwordx4 v[254:255], off
	v_mfma_f32_32x32x16_bf16 v[2:17], v[114:117], v[110:113], v[2:17]
	s_mov_b32 m0, s1
	s_waitcnt lgkmcnt(0)
	ds_read_b128 v[102:105], v98 offset:16384
	ds_read_b128 v[106:109], v99
	ds_read_b128 v[110:113], v99 offset:4096
	ds_read_b128 v[114:117], v98 offset:20480
	v_mfma_f32_32x32x16_bf16 v[34:49], v[238:241], v[242:245], v[34:49]
	v_mfma_f32_32x32x16_bf16 v[18:33], v[238:241], v[246:249], v[18:33]
	v_mfma_f32_32x32x16_bf16 v[50:65], v[250:253], v[242:245], v[50:65]
	v_mfma_f32_32x32x16_bf16 v[2:17], v[250:253], v[246:249], v[2:17]
	s_waitcnt lgkmcnt(0)
	ds_read_b128 v[238:241], v100 offset:16384
	ds_read_b128 v[242:245], v101
	ds_read_b128 v[246:249], v101 offset:4096
	ds_read_b128 v[250:253], v100 offset:20480
	v_mfma_f32_32x32x16_bf16 v[34:49], v[102:105], v[106:109], v[34:49]
	v_mfma_f32_32x32x16_bf16 v[18:33], v[102:105], v[110:113], v[18:33]
	v_mfma_f32_32x32x16_bf16 v[50:65], v[114:117], v[106:109], v[50:65]
	v_mfma_f32_32x32x16_bf16 v[2:17], v[114:117], v[110:113], v[2:17]
	s_waitcnt vmcnt(0) lgkmcnt(0)
	s_barrier
; template <class Epi>
; DI void gemm_phase(const u16* __restrict__ A, const u16* __restrict__ B, int mtiles, int ntiles, char* lds, const Epi& epi) {
;     ...
;         for (int kt = 0; kt < 16; ++kt) {
;             if (kt + 1 < 16) GSTAGE((kt + 1) & 1, kt + 1, ga, gb);
;             const char* sa = lds + (kt & 1) * 32768; const char* sb = sa + 16384;
; #pragma unroll
;             for (int ks = 0; ks < 4; ++ks) {
;                 bf16x8 fw[2], fx[2];
; #pragma unroll
;                 for (int ct = 0; ct < 2; ++ct) fw[ct] = *(const bf16x8*)(sb + swz(wn * 64 + ct * 32 + r, 2 * ks + h));
; #pragma unroll
;                 for (int tt = 0; tt < 2; ++tt) fx[tt] = *(const bf16x8*)(sa + swz(wm * 64 + tt * 32 + r, 2 * ks + h));
; #pragma unroll
;                 for (int ct = 0; ct < 2; ++ct)
; #pragma unroll
;                     for (int tt = 0; tt < 2; ++tt) acc[ct][tt] = __builtin_amdgcn_mfma_f32_32x32x16_bf16(fw[ct], fx[tt], acc[ct][tt], 0, 0, 0);
;             }
;             __syncthreads();
;         }
	ds_read_b128 v[102:105], v74 offset:49152
	ds_read_b128 v[106:109], v96 offset:32768
	ds_read_b128 v[110:113], v96 offset:36864
	ds_read_b128 v[114:117], v74 offset:53248
	v_mfma_f32_32x32x16_bf16 v[34:49], v[238:241], v[242:245], v[34:49]
	v_mfma_f32_32x32x16_bf16 v[18:33], v[238:241], v[246:249], v[18:33]
	v_lshl_add_u64 v[254:255], v[76:77], 0, s[18:19]
	global_load_lds_dwordx4 v[254:255], off
	v_lshl_add_u64 v[254:255], v[78:79], 0, s[18:19]
	s_mov_b32 m0, s7
	s_nop 0
	global_load_lds_dwordx4 v[254:255], off
	v_lshl_add_u64 v[254:255], v[80:81], 0, s[18:19]
	s_mov_b32 m0, s38
	v_mfma_f32_32x32x16_bf16 v[50:65], v[250:253], v[242:245], v[50:65]
	global_load_lds_dwordx4 v[254:255], off
	v_lshl_add_u64 v[254:255], v[82:83], 0, s[18:19]
	s_mov_b32 m0, s39
	s_nop 0
	global_load_lds_dwordx4 v[254:255], off
	v_lshl_add_u64 v[254:255], v[84:85], 0, s[18:19]
	s_mov_b32 m0, s50
	v_mfma_f32_32x32x16_bf16 v[2:17], v[250:253], v[246:249], v[2:17]
	global_load_lds_dwordx4 v[254:255], off
	s_waitcnt lgkmcnt(0)
	ds_read_b128 v[238:241], v95 offset:49152
	ds_read_b128 v[242:245], v97 offset:32768
	ds_read_b128 v[246:249], v97 offset:36864
	ds_read_b128 v[250:253], v95 offset:53248
	v_mfma_f32_32x32x16_bf16 v[34:49], v[102:105], v[106:109], v[34:49]
	v_lshl_add_u64 v[254:255], v[86:87], 0, s[18:19]
	s_mov_b32 m0, s51
	s_nop 0
	global_load_lds_dwordx4 v[254:255], off
	v_mfma_f32_32x32x16_bf16 v[18:33], v[102:105], v[110:113], v[18:33]
	v_lshl_add_u64 v[254:255], v[88:89], 0, s[18:19]
	s_mov_b32 m0, s83
	s_nop 0
	global_load_lds_dwordx4 v[254:255], off
	v_mfma_f32_32x32x16_bf16 v[50:65], v[114:117], v[106:109], v[50:65]
	v_lshl_add_u64 v[254:255], v[90:91], 0, s[18:19]
	s_mov_b32 m0, s90
	s_nop 0
	global_load_lds_dwordx4 v[254:255], off
	v_mfma_f32_32x32x16_bf16 v[2:17], v[114:117], v[110:113], v[2:17]
	s_mov_b32 m0, s86
	s_waitcnt lgkmcnt(0)
	ds_read_b128 v[102:105], v98 offset:49152
	ds_read_b128 v[106:109], v99 offset:32768
	ds_read_b128 v[110:113], v99 offset:36864
	ds_read_b128 v[114:117], v98 offset:53248
	v_mfma_f32_32x32x16_bf16 v[34:49], v[238:241], v[242:245], v[34:49]
	v_mfma_f32_32x32x16_bf16 v[18:33], v[238:241], v[246:249], v[18:33]
	v_mfma_f32_32x32x16_bf16 v[50:65], v[250:253], v[242:245], v[50:65]
	v_mfma_f32_32x32x16_bf16 v[2:17], v[250:253], v[246:249], v[2:17]
	s_waitcnt lgkmcnt(0)
	ds_read_b128 v[238:241], v100 offset:49152
	ds_read_b128 v[242:245], v101 offset:32768
	ds_read_b128 v[246:249], v101 offset:36864
	ds_read_b128 v[250:253], v100 offset:53248
	v_mfma_f32_32x32x16_bf16 v[34:49], v[102:105], v[106:109], v[34:49]
	v_mfma_f32_32x32x16_bf16 v[18:33], v[102:105], v[110:113], v[18:33]
	v_mfma_f32_32x32x16_bf16 v[50:65], v[114:117], v[106:109], v[50:65]
	v_mfma_f32_32x32x16_bf16 v[2:17], v[114:117], v[110:113], v[2:17]
	s_waitcnt vmcnt(0) lgkmcnt(0)
	s_barrier
	ds_read_b128 v[102:105], v74 offset:16384
	ds_read_b128 v[106:109], v96
	ds_read_b128 v[110:113], v96 offset:4096
	ds_read_b128 v[114:117], v74 offset:20480
	v_mfma_f32_32x32x16_bf16 v[34:49], v[238:241], v[242:245], v[34:49]
	v_mfma_f32_32x32x16_bf16 v[18:33], v[238:241], v[246:249], v[18:33]
	v_lshl_add_u64 v[254:255], v[76:77], 0, s[20:21]
	global_load_lds_dwordx4 v[254:255], off
	v_lshl_add_u64 v[254:255], v[78:79], 0, s[20:21]
	s_mov_b32 m0, s87
	s_nop 0
	global_load_lds_dwordx4 v[254:255], off
	v_lshl_add_u64 v[254:255], v[80:81], 0, s[20:21]
	s_mov_b32 m0, s88
	v_mfma_f32_32x32x16_bf16 v[50:65], v[250:253], v[242:245], v[50:65]
	global_load_lds_dwordx4 v[254:255], off
	v_lshl_add_u64 v[254:255], v[82:83], 0, s[20:21]
	s_mov_b32 m0, s89
	s_nop 0
	global_load_lds_dwordx4 v[254:255], off
	v_lshl_add_u64 v[254:255], v[84:85], 0, s[20:21]
	s_mov_b32 m0, s91
	v_mfma_f32_32x32x16_bf16 v[2:17], v[250:253], v[246:249], v[2:17]
	global_load_lds_dwordx4 v[254:255], off
	s_waitcnt lgkmcnt(0)
	ds_read_b128 v[238:241], v95 offset:16384
	ds_read_b128 v[242:245], v97
	ds_read_b128 v[246:249], v97 offset:4096
	ds_read_b128 v[250:253], v95 offset:20480
	v_mfma_f32_32x32x16_bf16 v[34:49], v[102:105], v[106:109], v[34:49]
	v_lshl_add_u64 v[254:255], v[86:87], 0, s[20:21]
	s_mov_b32 m0, s92
	s_nop 0
	global_load_lds_dwordx4 v[254:255], off
	v_mfma_f32_32x32x16_bf16 v[18:33], v[102:105], v[110:113], v[18:33]
	v_lshl_add_u64 v[254:255], v[88:89], 0, s[20:21]
	s_mov_b32 m0, s93
	s_nop 0
	global_load_lds_dwordx4 v[254:255], off
	v_mfma_f32_32x32x16_bf16 v[50:65], v[114:117], v[106:109], v[50:65]
	v_lshl_add_u64 v[254:255], v[90:91], 0, s[20:21]
	s_mov_b32 m0, s94
	s_nop 0
	global_load_lds_dwordx4 v[254:255], off
	v_mfma_f32_32x32x16_bf16 v[2:17], v[114:117], v[110:113], v[2:17]
	s_mov_b32 m0, s1
	s_waitcnt lgkmcnt(0)
	ds_read_b128 v[102:105], v98 offset:16384
	ds_read_b128 v[106:109], v99
	ds_read_b128 v[110:113], v99 offset:4096
	ds_read_b128 v[114:117], v98 offset:20480
	v_mfma_f32_32x32x16_bf16 v[34:49], v[238:241], v[242:245], v[34:49]
	v_mfma_f32_32x32x16_bf16 v[18:33], v[238:241], v[246:249], v[18:33]
	v_mfma_f32_32x32x16_bf16 v[50:65], v[250:253], v[242:245], v[50:65]
	v_mfma_f32_32x32x16_bf16 v[2:17], v[250:253], v[246:249], v[2:17]
	s_waitcnt lgkmcnt(0)
	ds_read_b128 v[238:241], v100 offset:16384
	ds_read_b128 v[242:245], v101
	ds_read_b128 v[246:249], v101 offset:4096
	ds_read_b128 v[250:253], v100 offset:20480
	v_mfma_f32_32x32x16_bf16 v[34:49], v[102:105], v[106:109], v[34:49]
	v_mfma_f32_32x32x16_bf16 v[18:33], v[102:105], v[110:113], v[18:33]
	v_mfma_f32_32x32x16_bf16 v[50:65], v[114:117], v[106:109], v[50:65]
	v_mfma_f32_32x32x16_bf16 v[2:17], v[114:117], v[110:113], v[2:17]
	s_waitcnt vmcnt(0) lgkmcnt(0)
	s_barrier
; template <class Epi>
; DI void gemm_phase(const u16* __restrict__ A, const u16* __restrict__ B, int mtiles, int ntiles, char* lds, const Epi& epi) {
;     ...
;         for (int kt = 0; kt < 16; ++kt) {
;             if (kt + 1 < 16) GSTAGE((kt + 1) & 1, kt + 1, ga, gb);
;             const char* sa = lds + (kt & 1) * 32768; const char* sb = sa + 16384;
; #pragma unroll
;             for (int ks = 0; ks < 4; ++ks) {
;                 bf16x8 fw[2], fx[2];
; #pragma unroll
;                 for (int ct = 0; ct < 2; ++ct) fw[ct] = *(const bf16x8*)(sb + swz(wn * 64 + ct * 32 + r, 2 * ks + h));
; #pragma unroll
;                 for (int tt = 0; tt < 2; ++tt) fx[tt] = *(const bf16x8*)(sa + swz(wm * 64 + tt * 32 + r, 2 * ks + h));
; #pragma unroll
;                 for (int ct = 0; ct < 2; ++ct)
; #pragma unroll
;                     for (int tt = 0; tt < 2; ++tt) acc[ct][tt] = __builtin_amdgcn_mfma_f32_32x32x16_bf16(fw[ct], fx[tt], acc[ct][tt], 0, 0, 0);
;             }
;             __syncthreads();
;         }
	ds_read_b128 v[102:105], v74 offset:49152
	ds_read_b128 v[106:109], v96 offset:32768
	ds_read_b128 v[110:113], v96 offset:36864
	ds_read_b128 v[114:117], v74 offset:53248
	v_mfma_f32_32x32x16_bf16 v[34:49], v[238:241], v[242:245], v[34:49]
	v_mfma_f32_32x32x16_bf16 v[18:33], v[238:241], v[246:249], v[18:33]
	v_lshl_add_u64 v[254:255], v[76:77], 0, s[22:23]
	global_load_lds_dwordx4 v[254:255], off
	v_lshl_add_u64 v[254:255], v[78:79], 0, s[22:23]
	s_mov_b32 m0, s7
	s_nop 0
	global_load_lds_dwordx4 v[254:255], off
	v_lshl_add_u64 v[254:255], v[80:81], 0, s[22:23]
	s_mov_b32 m0, s38
	v_mfma_f32_32x32x16_bf16 v[50:65], v[250:253], v[242:245], v[50:65]
	global_load_lds_dwordx4 v[254:255], off
	v_lshl_add_u64 v[254:255], v[82:83], 0, s[22:23]
	s_mov_b32 m0, s39
	s_nop 0
	global_load_lds_dwordx4 v[254:255], off
	v_lshl_add_u64 v[254:255], v[84:85], 0, s[22:23]
	s_mov_b32 m0, s50
	v_mfma_f32_32x32x16_bf16 v[2:17], v[250:253], v[246:249], v[2:17]
	global_load_lds_dwordx4 v[254:255], off
	s_waitcnt lgkmcnt(0)
	ds_read_b128 v[238:241], v95 offset:49152
	ds_read_b128 v[242:245], v97 offset:32768
	ds_read_b128 v[246:249], v97 offset:36864
	ds_read_b128 v[250:253], v95 offset:53248
	v_mfma_f32_32x32x16_bf16 v[34:49], v[102:105], v[106:109], v[34:49]
	v_lshl_add_u64 v[254:255], v[86:87], 0, s[22:23]
	s_mov_b32 m0, s51
	s_nop 0
	global_load_lds_dwordx4 v[254:255], off
	v_mfma_f32_32x32x16_bf16 v[18:33], v[102:105], v[110:113], v[18:33]
	v_lshl_add_u64 v[254:255], v[88:89], 0, s[22:23]
	s_mov_b32 m0, s83
	s_nop 0
	global_load_lds_dwordx4 v[254:255], off
	v_mfma_f32_32x32x16_bf16 v[50:65], v[114:117], v[106:109], v[50:65]
	v_lshl_add_u64 v[254:255], v[90:91], 0, s[22:23]
	s_mov_b32 m0, s90
	s_nop 0
	global_load_lds_dwordx4 v[254:255], off
	v_mfma_f32_32x32x16_bf16 v[2:17], v[114:117], v[110:113], v[2:17]
	s_mov_b32 m0, s86
	s_waitcnt lgkmcnt(0)
	ds_read_b128 v[102:105], v98 offset:49152
	ds_read_b128 v[106:109], v99 offset:32768
	ds_read_b128 v[110:113], v99 offset:36864
	ds_read_b128 v[114:117], v98 offset:53248
	v_mfma_f32_32x32x16_bf16 v[34:49], v[238:241], v[242:245], v[34:49]
	v_mfma_f32_32x32x16_bf16 v[18:33], v[238:241], v[246:249], v[18:33]
	v_mfma_f32_32x32x16_bf16 v[50:65], v[250:253], v[242:245], v[50:65]
	v_mfma_f32_32x32x16_bf16 v[2:17], v[250:253], v[246:249], v[2:17]
	s_waitcnt lgkmcnt(0)
	ds_read_b128 v[238:241], v100 offset:49152
	ds_read_b128 v[242:245], v101 offset:32768
	ds_read_b128 v[246:249], v101 offset:36864
	ds_read_b128 v[250:253], v100 offset:53248
	v_mfma_f32_32x32x16_bf16 v[34:49], v[102:105], v[106:109], v[34:49]
	v_mfma_f32_32x32x16_bf16 v[18:33], v[102:105], v[110:113], v[18:33]
	v_mfma_f32_32x32x16_bf16 v[50:65], v[114:117], v[106:109], v[50:65]
	v_mfma_f32_32x32x16_bf16 v[2:17], v[114:117], v[110:113], v[2:17]
	s_waitcnt vmcnt(0) lgkmcnt(0)
	s_barrier
	ds_read_b128 v[102:105], v74 offset:16384
	ds_read_b128 v[106:109], v96
	ds_read_b128 v[110:113], v96 offset:4096
	ds_read_b128 v[114:117], v74 offset:20480
	v_mfma_f32_32x32x16_bf16 v[34:49], v[238:241], v[242:245], v[34:49]
	v_mfma_f32_32x32x16_bf16 v[18:33], v[238:241], v[246:249], v[18:33]
	v_lshl_add_u64 v[254:255], v[76:77], 0, s[24:25]
	global_load_lds_dwordx4 v[254:255], off
	v_lshl_add_u64 v[254:255], v[78:79], 0, s[24:25]
	s_mov_b32 m0, s87
	s_nop 0
	global_load_lds_dwordx4 v[254:255], off
	v_lshl_add_u64 v[254:255], v[80:81], 0, s[24:25]
	s_mov_b32 m0, s88
	v_mfma_f32_32x32x16_bf16 v[50:65], v[250:253], v[242:245], v[50:65]
	global_load_lds_dwordx4 v[254:255], off
	v_lshl_add_u64 v[254:255], v[82:83], 0, s[24:25]
	s_mov_b32 m0, s89
	s_nop 0
	global_load_lds_dwordx4 v[254:255], off
	v_lshl_add_u64 v[254:255], v[84:85], 0, s[24:25]
	s_mov_b32 m0, s91
	v_mfma_f32_32x32x16_bf16 v[2:17], v[250:253], v[246:249], v[2:17]
	global_load_lds_dwordx4 v[254:255], off
	s_waitcnt lgkmcnt(0)
	ds_read_b128 v[238:241], v95 offset:16384
	ds_read_b128 v[242:245], v97
	ds_read_b128 v[246:249], v97 offset:4096
	ds_read_b128 v[250:253], v95 offset:20480
	v_mfma_f32_32x32x16_bf16 v[34:49], v[102:105], v[106:109], v[34:49]
	v_lshl_add_u64 v[254:255], v[86:87], 0, s[24:25]
	s_mov_b32 m0, s92
	s_nop 0
	global_load_lds_dwordx4 v[254:255], off
	v_mfma_f32_32x32x16_bf16 v[18:33], v[102:105], v[110:113], v[18:33]
	v_lshl_add_u64 v[254:255], v[88:89], 0, s[24:25]
	s_mov_b32 m0, s93
	s_nop 0
	global_load_lds_dwordx4 v[254:255], off
	v_mfma_f32_32x32x16_bf16 v[50:65], v[114:117], v[106:109], v[50:65]
	v_lshl_add_u64 v[254:255], v[90:91], 0, s[24:25]
	s_mov_b32 m0, s94
	s_nop 0
	global_load_lds_dwordx4 v[254:255], off
	v_mfma_f32_32x32x16_bf16 v[2:17], v[114:117], v[110:113], v[2:17]
	s_mov_b32 m0, s1
	s_waitcnt lgkmcnt(0)
	ds_read_b128 v[102:105], v98 offset:16384
	ds_read_b128 v[106:109], v99
	ds_read_b128 v[110:113], v99 offset:4096
	ds_read_b128 v[114:117], v98 offset:20480
	v_mfma_f32_32x32x16_bf16 v[34:49], v[238:241], v[242:245], v[34:49]
	v_mfma_f32_32x32x16_bf16 v[18:33], v[238:241], v[246:249], v[18:33]
	v_mfma_f32_32x32x16_bf16 v[50:65], v[250:253], v[242:245], v[50:65]
	v_mfma_f32_32x32x16_bf16 v[2:17], v[250:253], v[246:249], v[2:17]
	s_waitcnt lgkmcnt(0)
	ds_read_b128 v[238:241], v100 offset:16384
	ds_read_b128 v[242:245], v101
	ds_read_b128 v[246:249], v101 offset:4096
	ds_read_b128 v[250:253], v100 offset:20480
	v_mfma_f32_32x32x16_bf16 v[34:49], v[102:105], v[106:109], v[34:49]
	v_mfma_f32_32x32x16_bf16 v[18:33], v[102:105], v[110:113], v[18:33]
	v_mfma_f32_32x32x16_bf16 v[50:65], v[114:117], v[106:109], v[50:65]
	v_mfma_f32_32x32x16_bf16 v[2:17], v[114:117], v[110:113], v[2:17]
	s_waitcnt vmcnt(0) lgkmcnt(0)
	s_barrier
; template <class Epi>
; DI void gemm_phase(const u16* __restrict__ A, const u16* __restrict__ B, int mtiles, int ntiles, char* lds, const Epi& epi) {
;     ...
;         for (int kt = 0; kt < 16; ++kt) {
;             if (kt + 1 < 16) GSTAGE((kt + 1) & 1, kt + 1, ga, gb);
;             const char* sa = lds + (kt & 1) * 32768; const char* sb = sa + 16384;
; #pragma unroll
;             for (int ks = 0; ks < 4; ++ks) {
;                 bf16x8 fw[2], fx[2];
; #pragma unroll
;                 for (int ct = 0; ct < 2; ++ct) fw[ct] = *(const bf16x8*)(sb + swz(wn * 64 + ct * 32 + r, 2 * ks + h));
; #pragma unroll
;                 for (int tt = 0; tt < 2; ++tt) fx[tt] = *(const bf16x8*)(sa + swz(wm * 64 + tt * 32 + r, 2 * ks + h));
; #pragma unroll
;                 for (int ct = 0; ct < 2; ++ct)
; #pragma unroll
;                     for (int tt = 0; tt < 2; ++tt) acc[ct][tt] = __builtin_amdgcn_mfma_f32_32x32x16_bf16(fw[ct], fx[tt], acc[ct][tt], 0, 0, 0);
;             }
;             __syncthreads();
;         }
	ds_read_b128 v[102:105], v74 offset:49152
	ds_read_b128 v[106:109], v96 offset:32768
	ds_read_b128 v[110:113], v96 offset:36864
	ds_read_b128 v[114:117], v74 offset:53248
	v_mfma_f32_32x32x16_bf16 v[34:49], v[238:241], v[242:245], v[34:49]
	v_mfma_f32_32x32x16_bf16 v[18:33], v[238:241], v[246:249], v[18:33]
	v_lshl_add_u64 v[254:255], v[76:77], 0, s[26:27]
	global_load_lds_dwordx4 v[254:255], off
	v_lshl_add_u64 v[254:255], v[78:79], 0, s[26:27]
	s_mov_b32 m0, s7
	s_nop 0
	global_load_lds_dwordx4 v[254:255], off
	v_lshl_add_u64 v[254:255], v[80:81], 0, s[26:27]
	s_mov_b32 m0, s38
	v_mfma_f32_32x32x16_bf16 v[50:65], v[250:253], v[242:245], v[50:65]
	global_load_lds_dwordx4 v[254:255], off
	v_lshl_add_u64 v[254:255], v[82:83], 0, s[26:27]
	s_mov_b32 m0, s39
	s_nop 0
	global_load_lds_dwordx4 v[254:255], off
	v_lshl_add_u64 v[254:255], v[84:85], 0, s[26:27]
	s_mov_b32 m0, s50
	v_mfma_f32_32x32x16_bf16 v[2:17], v[250:253], v[246:249], v[2:17]
	global_load_lds_dwordx4 v[254:255], off
	s_waitcnt lgkmcnt(0)
	ds_read_b128 v[238:241], v95 offset:49152
	ds_read_b128 v[242:245], v97 offset:32768
	ds_read_b128 v[246:249], v97 offset:36864
	ds_read_b128 v[250:253], v95 offset:53248
	v_mfma_f32_32x32x16_bf16 v[34:49], v[102:105], v[106:109], v[34:49]
	v_lshl_add_u64 v[254:255], v[86:87], 0, s[26:27]
	s_mov_b32 m0, s51
	s_nop 0
	global_load_lds_dwordx4 v[254:255], off
	v_mfma_f32_32x32x16_bf16 v[18:33], v[102:105], v[110:113], v[18:33]
	v_lshl_add_u64 v[254:255], v[88:89], 0, s[26:27]
	s_mov_b32 m0, s83
	s_nop 0
	global_load_lds_dwordx4 v[254:255], off
	v_mfma_f32_32x32x16_bf16 v[50:65], v[114:117], v[106:109], v[50:65]
	v_lshl_add_u64 v[254:255], v[90:91], 0, s[26:27]
	s_mov_b32 m0, s90
	s_nop 0
	global_load_lds_dwordx4 v[254:255], off
	v_mfma_f32_32x32x16_bf16 v[2:17], v[114:117], v[110:113], v[2:17]
	s_mov_b32 m0, s86
	s_waitcnt lgkmcnt(0)
	ds_read_b128 v[102:105], v98 offset:49152
	ds_read_b128 v[106:109], v99 offset:32768
	ds_read_b128 v[110:113], v99 offset:36864
	ds_read_b128 v[114:117], v98 offset:53248
	v_mfma_f32_32x32x16_bf16 v[34:49], v[238:241], v[242:245], v[34:49]
	v_mfma_f32_32x32x16_bf16 v[18:33], v[238:241], v[246:249], v[18:33]
	v_mfma_f32_32x32x16_bf16 v[50:65], v[250:253], v[242:245], v[50:65]
	v_mfma_f32_32x32x16_bf16 v[2:17], v[250:253], v[246:249], v[2:17]
	s_waitcnt lgkmcnt(0)
	ds_read_b128 v[238:241], v100 offset:49152
	ds_read_b128 v[242:245], v101 offset:32768
	ds_read_b128 v[246:249], v101 offset:36864
	ds_read_b128 v[250:253], v100 offset:53248
	v_mfma_f32_32x32x16_bf16 v[34:49], v[102:105], v[106:109], v[34:49]
	v_mfma_f32_32x32x16_bf16 v[18:33], v[102:105], v[110:113], v[18:33]
	v_mfma_f32_32x32x16_bf16 v[50:65], v[114:117], v[106:109], v[50:65]
	v_mfma_f32_32x32x16_bf16 v[2:17], v[114:117], v[110:113], v[2:17]
	s_waitcnt vmcnt(0) lgkmcnt(0)
	s_barrier
	ds_read_b128 v[102:105], v74 offset:16384
	ds_read_b128 v[106:109], v96
	ds_read_b128 v[110:113], v96 offset:4096
	ds_read_b128 v[114:117], v74 offset:20480
	v_mfma_f32_32x32x16_bf16 v[34:49], v[238:241], v[242:245], v[34:49]
	v_mfma_f32_32x32x16_bf16 v[18:33], v[238:241], v[246:249], v[18:33]
	v_lshl_add_u64 v[254:255], v[76:77], 0, s[28:29]
	global_load_lds_dwordx4 v[254:255], off
	v_lshl_add_u64 v[254:255], v[78:79], 0, s[28:29]
	s_mov_b32 m0, s87
	s_nop 0
	global_load_lds_dwordx4 v[254:255], off
	v_lshl_add_u64 v[254:255], v[80:81], 0, s[28:29]
	s_mov_b32 m0, s88
	v_mfma_f32_32x32x16_bf16 v[50:65], v[250:253], v[242:245], v[50:65]
	global_load_lds_dwordx4 v[254:255], off
	v_lshl_add_u64 v[254:255], v[82:83], 0, s[28:29]
	s_mov_b32 m0, s89
	s_nop 0
	global_load_lds_dwordx4 v[254:255], off
	v_lshl_add_u64 v[254:255], v[84:85], 0, s[28:29]
	s_mov_b32 m0, s91
	v_mfma_f32_32x32x16_bf16 v[2:17], v[250:253], v[246:249], v[2:17]
	global_load_lds_dwordx4 v[254:255], off
	s_waitcnt lgkmcnt(0)
	ds_read_b128 v[238:241], v95 offset:16384
	ds_read_b128 v[242:245], v97
	ds_read_b128 v[246:249], v97 offset:4096
	ds_read_b128 v[250:253], v95 offset:20480
	v_mfma_f32_32x32x16_bf16 v[34:49], v[102:105], v[106:109], v[34:49]
	v_lshl_add_u64 v[254:255], v[86:87], 0, s[28:29]
	s_mov_b32 m0, s92
	s_nop 0
	global_load_lds_dwordx4 v[254:255], off
	v_mfma_f32_32x32x16_bf16 v[18:33], v[102:105], v[110:113], v[18:33]
	v_lshl_add_u64 v[254:255], v[88:89], 0, s[28:29]
	s_mov_b32 m0, s93
	s_nop 0
	global_load_lds_dwordx4 v[254:255], off
	v_mfma_f32_32x32x16_bf16 v[50:65], v[114:117], v[106:109], v[50:65]
	v_lshl_add_u64 v[254:255], v[90:91], 0, s[28:29]
	s_mov_b32 m0, s94
	s_nop 0
	global_load_lds_dwordx4 v[254:255], off
	v_mfma_f32_32x32x16_bf16 v[2:17], v[114:117], v[110:113], v[2:17]
	s_mov_b32 m0, s1
	s_waitcnt lgkmcnt(0)
	ds_read_b128 v[102:105], v98 offset:16384
	ds_read_b128 v[106:109], v99
	ds_read_b128 v[110:113], v99 offset:4096
	ds_read_b128 v[114:117], v98 offset:20480
	v_mfma_f32_32x32x16_bf16 v[34:49], v[238:241], v[242:245], v[34:49]
	v_mfma_f32_32x32x16_bf16 v[18:33], v[238:241], v[246:249], v[18:33]
	v_mfma_f32_32x32x16_bf16 v[50:65], v[250:253], v[242:245], v[50:65]
	v_mfma_f32_32x32x16_bf16 v[2:17], v[250:253], v[246:249], v[2:17]
	s_waitcnt lgkmcnt(0)
	ds_read_b128 v[238:241], v100 offset:16384
	ds_read_b128 v[242:245], v101
	ds_read_b128 v[246:249], v101 offset:4096
	ds_read_b128 v[250:253], v100 offset:20480
	v_mfma_f32_32x32x16_bf16 v[34:49], v[102:105], v[106:109], v[34:49]
	v_mfma_f32_32x32x16_bf16 v[18:33], v[102:105], v[110:113], v[18:33]
	v_mfma_f32_32x32x16_bf16 v[50:65], v[114:117], v[106:109], v[50:65]
	v_mfma_f32_32x32x16_bf16 v[2:17], v[114:117], v[110:113], v[2:17]
	s_waitcnt vmcnt(0) lgkmcnt(0)
	s_barrier
; template <class Epi>
; DI void gemm_phase(const u16* __restrict__ A, const u16* __restrict__ B, int mtiles, int ntiles, char* lds, const Epi& epi) {
;     ...
;         for (int kt = 0; kt < 16; ++kt) {
;             if (kt + 1 < 16) GSTAGE((kt + 1) & 1, kt + 1, ga, gb);
;             const char* sa = lds + (kt & 1) * 32768; const char* sb = sa + 16384;
; #pragma unroll
;             for (int ks = 0; ks < 4; ++ks) {
;                 bf16x8 fw[2], fx[2];
; #pragma unroll
;                 for (int ct = 0; ct < 2; ++ct) fw[ct] = *(const bf16x8*)(sb + swz(wn * 64 + ct * 32 + r, 2 * ks + h));
; #pragma unroll
;                 for (int tt = 0; tt < 2; ++tt) fx[tt] = *(const bf16x8*)(sa + swz(wm * 64 + tt * 32 + r, 2 * ks + h));
; #pragma unroll
;                 for (int ct = 0; ct < 2; ++ct)
; #pragma unroll
;                     for (int tt = 0; tt < 2; ++tt) acc[ct][tt] = __builtin_amdgcn_mfma_f32_32x32x16_bf16(fw[ct], fx[tt], acc[ct][tt], 0, 0, 0);
;             }
;             __syncthreads();
;         }
	ds_read_b128 v[102:105], v74 offset:49152
	ds_read_b128 v[106:109], v96 offset:32768
	ds_read_b128 v[110:113], v96 offset:36864
	ds_read_b128 v[114:117], v74 offset:53248
	v_mfma_f32_32x32x16_bf16 v[34:49], v[238:241], v[242:245], v[34:49]
	v_mfma_f32_32x32x16_bf16 v[18:33], v[238:241], v[246:249], v[18:33]
	v_lshl_add_u64 v[254:255], v[76:77], 0, s[30:31]
	global_load_lds_dwordx4 v[254:255], off
	v_lshl_add_u64 v[254:255], v[78:79], 0, s[30:31]
	s_mov_b32 m0, s7
	s_nop 0
	global_load_lds_dwordx4 v[254:255], off
	v_lshl_add_u64 v[254:255], v[80:81], 0, s[30:31]
	s_mov_b32 m0, s38
	v_mfma_f32_32x32x16_bf16 v[50:65], v[250:253], v[242:245], v[50:65]
	global_load_lds_dwordx4 v[254:255], off
	v_lshl_add_u64 v[254:255], v[82:83], 0, s[30:31]
	s_mov_b32 m0, s39
	s_nop 0
	global_load_lds_dwordx4 v[254:255], off
	v_lshl_add_u64 v[254:255], v[84:85], 0, s[30:31]
	s_mov_b32 m0, s50
	v_mfma_f32_32x32x16_bf16 v[2:17], v[250:253], v[246:249], v[2:17]
	global_load_lds_dwordx4 v[254:255], off
	s_waitcnt lgkmcnt(0)
	ds_read_b128 v[238:241], v95 offset:49152
	ds_read_b128 v[242:245], v97 offset:32768
	ds_read_b128 v[246:249], v97 offset:36864
	ds_read_b128 v[250:253], v95 offset:53248
	v_mfma_f32_32x32x16_bf16 v[34:49], v[102:105], v[106:109], v[34:49]
	v_lshl_add_u64 v[254:255], v[86:87], 0, s[30:31]
	s_mov_b32 m0, s51
	s_nop 0
	global_load_lds_dwordx4 v[254:255], off
	v_mfma_f32_32x32x16_bf16 v[18:33], v[102:105], v[110:113], v[18:33]
	v_lshl_add_u64 v[254:255], v[88:89], 0, s[30:31]
	s_mov_b32 m0, s83
	s_nop 0
	global_load_lds_dwordx4 v[254:255], off
	v_mfma_f32_32x32x16_bf16 v[50:65], v[114:117], v[106:109], v[50:65]
	v_lshl_add_u64 v[254:255], v[90:91], 0, s[30:31]
	s_mov_b32 m0, s90
	s_nop 0
	global_load_lds_dwordx4 v[254:255], off
	v_mfma_f32_32x32x16_bf16 v[2:17], v[114:117], v[110:113], v[2:17]
	s_mov_b32 m0, s86
	s_waitcnt lgkmcnt(0)
	ds_read_b128 v[102:105], v98 offset:49152
	ds_read_b128 v[106:109], v99 offset:32768
	ds_read_b128 v[110:113], v99 offset:36864
	ds_read_b128 v[114:117], v98 offset:53248
	v_mfma_f32_32x32x16_bf16 v[34:49], v[238:241], v[242:245], v[34:49]
	v_mfma_f32_32x32x16_bf16 v[18:33], v[238:241], v[246:249], v[18:33]
	v_mfma_f32_32x32x16_bf16 v[50:65], v[250:253], v[242:245], v[50:65]
	v_mfma_f32_32x32x16_bf16 v[2:17], v[250:253], v[246:249], v[2:17]
	s_waitcnt lgkmcnt(0)
	ds_read_b128 v[238:241], v100 offset:49152
	ds_read_b128 v[242:245], v101 offset:32768
	ds_read_b128 v[246:249], v101 offset:36864
	ds_read_b128 v[250:253], v100 offset:53248
	v_mfma_f32_32x32x16_bf16 v[34:49], v[102:105], v[106:109], v[34:49]
	v_mfma_f32_32x32x16_bf16 v[18:33], v[102:105], v[110:113], v[18:33]
	v_mfma_f32_32x32x16_bf16 v[50:65], v[114:117], v[106:109], v[50:65]
	v_mfma_f32_32x32x16_bf16 v[2:17], v[114:117], v[110:113], v[2:17]
	s_waitcnt vmcnt(0) lgkmcnt(0)
	s_barrier
	ds_read_b128 v[102:105], v74 offset:16384
	ds_read_b128 v[106:109], v96
	ds_read_b128 v[110:113], v96 offset:4096
	ds_read_b128 v[114:117], v74 offset:20480
	v_mfma_f32_32x32x16_bf16 v[34:49], v[238:241], v[242:245], v[34:49]
	v_mfma_f32_32x32x16_bf16 v[18:33], v[238:241], v[246:249], v[18:33]
	v_lshl_add_u64 v[254:255], v[76:77], 0, s[36:37]
	global_load_lds_dwordx4 v[254:255], off
	v_lshl_add_u64 v[254:255], v[78:79], 0, s[36:37]
	s_mov_b32 m0, s87
	s_nop 0
	global_load_lds_dwordx4 v[254:255], off
	v_lshl_add_u64 v[254:255], v[80:81], 0, s[36:37]
	s_mov_b32 m0, s88
	v_mfma_f32_32x32x16_bf16 v[50:65], v[250:253], v[242:245], v[50:65]
	global_load_lds_dwordx4 v[254:255], off
	v_lshl_add_u64 v[254:255], v[82:83], 0, s[36:37]
	s_mov_b32 m0, s89
	s_nop 0
	global_load_lds_dwordx4 v[254:255], off
	v_lshl_add_u64 v[254:255], v[84:85], 0, s[36:37]
	s_mov_b32 m0, s91
	v_mfma_f32_32x32x16_bf16 v[2:17], v[250:253], v[246:249], v[2:17]
	global_load_lds_dwordx4 v[254:255], off
	s_waitcnt lgkmcnt(0)
	ds_read_b128 v[238:241], v95 offset:16384
	ds_read_b128 v[242:245], v97
	ds_read_b128 v[246:249], v97 offset:4096
	ds_read_b128 v[250:253], v95 offset:20480
	v_mfma_f32_32x32x16_bf16 v[34:49], v[102:105], v[106:109], v[34:49]
	v_lshl_add_u64 v[254:255], v[86:87], 0, s[36:37]
	s_mov_b32 m0, s92
	s_nop 0
	global_load_lds_dwordx4 v[254:255], off
	v_mfma_f32_32x32x16_bf16 v[18:33], v[102:105], v[110:113], v[18:33]
	v_lshl_add_u64 v[254:255], v[88:89], 0, s[36:37]
	s_mov_b32 m0, s93
	s_nop 0
	global_load_lds_dwordx4 v[254:255], off
	v_mfma_f32_32x32x16_bf16 v[50:65], v[114:117], v[106:109], v[50:65]
	v_lshl_add_u64 v[254:255], v[90:91], 0, s[36:37]
	s_mov_b32 m0, s94
	s_nop 0
	global_load_lds_dwordx4 v[254:255], off
	v_mfma_f32_32x32x16_bf16 v[2:17], v[114:117], v[110:113], v[2:17]
	s_mov_b32 m0, s1
	s_waitcnt lgkmcnt(0)
	ds_read_b128 v[102:105], v98 offset:16384
	ds_read_b128 v[106:109], v99
	ds_read_b128 v[110:113], v99 offset:4096
	ds_read_b128 v[114:117], v98 offset:20480
	v_mfma_f32_32x32x16_bf16 v[34:49], v[238:241], v[242:245], v[34:49]
	v_mfma_f32_32x32x16_bf16 v[18:33], v[238:241], v[246:249], v[18:33]
	v_mfma_f32_32x32x16_bf16 v[50:65], v[250:253], v[242:245], v[50:65]
	v_mfma_f32_32x32x16_bf16 v[2:17], v[250:253], v[246:249], v[2:17]
	s_waitcnt lgkmcnt(0)
	ds_read_b128 v[238:241], v100 offset:16384
	ds_read_b128 v[242:245], v101
	ds_read_b128 v[246:249], v101 offset:4096
	ds_read_b128 v[250:253], v100 offset:20480
	v_mfma_f32_32x32x16_bf16 v[34:49], v[102:105], v[106:109], v[34:49]
	v_mfma_f32_32x32x16_bf16 v[18:33], v[102:105], v[110:113], v[18:33]
	v_mfma_f32_32x32x16_bf16 v[50:65], v[114:117], v[106:109], v[50:65]
	v_mfma_f32_32x32x16_bf16 v[2:17], v[114:117], v[110:113], v[2:17]
	s_waitcnt vmcnt(0) lgkmcnt(0)
	s_barrier
; template <class Epi>
; DI void gemm_phase(const u16* __restrict__ A, const u16* __restrict__ B, int mtiles, int ntiles, char* lds, const Epi& epi) {
;     ...
;         for (int kt = 0; kt < 16; ++kt) {
;             if (kt + 1 < 16) GSTAGE((kt + 1) & 1, kt + 1, ga, gb);
;             const char* sa = lds + (kt & 1) * 32768; const char* sb = sa + 16384;
; #pragma unroll
;             for (int ks = 0; ks < 4; ++ks) {
;                 bf16x8 fw[2], fx[2];
; #pragma unroll
;                 for (int ct = 0; ct < 2; ++ct) fw[ct] = *(const bf16x8*)(sb + swz(wn * 64 + ct * 32 + r, 2 * ks + h));
; #pragma unroll
;                 for (int tt = 0; tt < 2; ++tt) fx[tt] = *(const bf16x8*)(sa + swz(wm * 64 + tt * 32 + r, 2 * ks + h));
; #pragma unroll
;                 for (int ct = 0; ct < 2; ++ct)
; #pragma unroll
;                     for (int tt = 0; tt < 2; ++tt) acc[ct][tt] = __builtin_amdgcn_mfma_f32_32x32x16_bf16(fw[ct], fx[tt], acc[ct][tt], 0, 0, 0);
;             }
;             __syncthreads();
;         }
	ds_read_b128 v[102:105], v74 offset:49152
	ds_read_b128 v[106:109], v96 offset:32768
	ds_read_b128 v[110:113], v96 offset:36864
	ds_read_b128 v[114:117], v74 offset:53248
	v_mfma_f32_32x32x16_bf16 v[34:49], v[238:241], v[242:245], v[34:49]
	v_mfma_f32_32x32x16_bf16 v[18:33], v[238:241], v[246:249], v[18:33]
	v_lshl_add_u64 v[254:255], v[76:77], 0, s[68:69]
	global_load_lds_dwordx4 v[254:255], off
	v_lshl_add_u64 v[254:255], v[78:79], 0, s[68:69]
	s_mov_b32 m0, s7
	v_lshl_add_u64 v[76:77], v[76:77], 0, s[70:71]
	global_load_lds_dwordx4 v[254:255], off
	v_lshl_add_u64 v[254:255], v[80:81], 0, s[68:69]
	s_mov_b32 m0, s38
	v_mfma_f32_32x32x16_bf16 v[50:65], v[250:253], v[242:245], v[50:65]
	global_load_lds_dwordx4 v[254:255], off
	v_lshl_add_u64 v[254:255], v[82:83], 0, s[68:69]
	s_mov_b32 m0, s39
	s_nop 0
	global_load_lds_dwordx4 v[254:255], off
	v_lshl_add_u64 v[254:255], v[84:85], 0, s[68:69]
	s_mov_b32 m0, s50
	v_mfma_f32_32x32x16_bf16 v[2:17], v[250:253], v[246:249], v[2:17]
	global_load_lds_dwordx4 v[254:255], off
	s_waitcnt lgkmcnt(0)
	ds_read_b128 v[238:241], v95 offset:49152
	ds_read_b128 v[242:245], v97 offset:32768
	ds_read_b128 v[246:249], v97 offset:36864
	ds_read_b128 v[250:253], v95 offset:53248
	v_mfma_f32_32x32x16_bf16 v[34:49], v[102:105], v[106:109], v[34:49]
	v_lshl_add_u64 v[254:255], v[86:87], 0, s[68:69]
	s_mov_b32 m0, s51
	s_nop 0
	global_load_lds_dwordx4 v[254:255], off
	v_mfma_f32_32x32x16_bf16 v[18:33], v[102:105], v[110:113], v[18:33]
	v_lshl_add_u64 v[254:255], v[88:89], 0, s[68:69]
	s_mov_b32 m0, s83
	s_nop 0
	global_load_lds_dwordx4 v[254:255], off
	v_mfma_f32_32x32x16_bf16 v[50:65], v[114:117], v[106:109], v[50:65]
	v_lshl_add_u64 v[254:255], v[90:91], 0, s[68:69]
	s_mov_b32 m0, s90
	s_nop 0
	global_load_lds_dwordx4 v[254:255], off
	v_mfma_f32_32x32x16_bf16 v[2:17], v[114:117], v[110:113], v[2:17]
	s_mov_b32 m0, s86
	s_mov_b32 s86, 0
	s_waitcnt lgkmcnt(0)
	ds_read_b128 v[102:105], v98 offset:49152
	ds_read_b128 v[106:109], v99 offset:32768
	ds_read_b128 v[110:113], v99 offset:36864
	ds_read_b128 v[114:117], v98 offset:53248
	v_mfma_f32_32x32x16_bf16 v[34:49], v[238:241], v[242:245], v[34:49]
	v_mfma_f32_32x32x16_bf16 v[18:33], v[238:241], v[246:249], v[18:33]
	v_mfma_f32_32x32x16_bf16 v[50:65], v[250:253], v[242:245], v[50:65]
	v_mfma_f32_32x32x16_bf16 v[2:17], v[250:253], v[246:249], v[2:17]
	s_waitcnt lgkmcnt(0)
	ds_read_b128 v[238:241], v100 offset:49152
	ds_read_b128 v[242:245], v101 offset:32768
	ds_read_b128 v[246:249], v101 offset:36864
	ds_read_b128 v[250:253], v100 offset:53248
	v_mfma_f32_32x32x16_bf16 v[34:49], v[102:105], v[106:109], v[34:49]
	v_mfma_f32_32x32x16_bf16 v[18:33], v[102:105], v[110:113], v[18:33]
	v_mfma_f32_32x32x16_bf16 v[50:65], v[114:117], v[106:109], v[50:65]
	v_mfma_f32_32x32x16_bf16 v[2:17], v[114:117], v[110:113], v[2:17]
	s_waitcnt vmcnt(0) lgkmcnt(0)
	s_barrier
	global_load_lds_dwordx4 v[76:77], off
	v_lshl_add_u64 v[76:77], v[78:79], 0, s[70:71]
	s_mov_b32 m0, s87
	v_mfma_f32_32x32x16_bf16 v[34:49], v[238:241], v[242:245], v[34:49]
	global_load_lds_dwordx4 v[76:77], off
	v_lshl_add_u64 v[76:77], v[80:81], 0, s[70:71]
	s_mov_b32 m0, s88
	s_mov_b32 s88, 0
	global_load_lds_dwordx4 v[76:77], off
	v_lshl_add_u64 v[76:77], v[82:83], 0, s[70:71]
	s_mov_b32 m0, s89
	v_mfma_f32_32x32x16_bf16 v[18:33], v[238:241], v[246:249], v[18:33]
	global_load_lds_dwordx4 v[76:77], off
	v_lshl_add_u64 v[76:77], v[84:85], 0, s[70:71]
	s_mov_b32 m0, s91
	s_nop 0
	global_load_lds_dwordx4 v[76:77], off
	v_lshl_add_u64 v[76:77], v[86:87], 0, s[70:71]
	s_mov_b32 m0, s92
	v_mfma_f32_32x32x16_bf16 v[50:65], v[250:253], v[242:245], v[50:65]
	global_load_lds_dwordx4 v[76:77], off
	v_lshl_add_u64 v[76:77], v[88:89], 0, s[70:71]
	s_mov_b32 m0, s93
	s_nop 0
	global_load_lds_dwordx4 v[76:77], off
	v_lshl_add_u64 v[76:77], v[90:91], 0, s[70:71]
	s_mov_b32 m0, s94
	v_mfma_f32_32x32x16_bf16 v[2:17], v[250:253], v[246:249], v[2:17]
	global_load_lds_dwordx4 v[76:77], off
	ds_read_b128 v[76:79], v74 offset:16384
	ds_read_b128 v[80:83], v96
	ds_read_b128 v[84:87], v96 offset:4096
	ds_read_b128 v[88:91], v74 offset:20480
	s_waitcnt lgkmcnt(0)
	v_mfma_f32_32x32x16_bf16 v[34:49], v[76:79], v[80:83], v[34:49]
	v_mfma_f32_32x32x16_bf16 v[18:33], v[76:79], v[84:87], v[18:33]
	v_mfma_f32_32x32x16_bf16 v[50:65], v[88:91], v[80:83], v[50:65]
	v_mfma_f32_32x32x16_bf16 v[2:17], v[88:91], v[84:87], v[2:17]
	ds_read_b128 v[76:79], v95 offset:16384
	ds_read_b128 v[80:83], v97
	ds_read_b128 v[84:87], v97 offset:4096
	ds_read_b128 v[88:91], v95 offset:20480
	s_waitcnt lgkmcnt(0)
	v_mfma_f32_32x32x16_bf16 v[34:49], v[76:79], v[80:83], v[34:49]
	v_mfma_f32_32x32x16_bf16 v[18:33], v[76:79], v[84:87], v[18:33]
	v_mfma_f32_32x32x16_bf16 v[50:65], v[88:91], v[80:83], v[50:65]
	v_mfma_f32_32x32x16_bf16 v[2:17], v[88:91], v[84:87], v[2:17]
	ds_read_b128 v[76:79], v98 offset:16384
	ds_read_b128 v[80:83], v99
	ds_read_b128 v[84:87], v99 offset:4096
	ds_read_b128 v[88:91], v98 offset:20480
	s_waitcnt lgkmcnt(0)
	v_mfma_f32_32x32x16_bf16 v[34:49], v[76:79], v[80:83], v[34:49]
	v_mfma_f32_32x32x16_bf16 v[18:33], v[76:79], v[84:87], v[18:33]
	v_mfma_f32_32x32x16_bf16 v[50:65], v[88:91], v[80:83], v[50:65]
	v_mfma_f32_32x32x16_bf16 v[2:17], v[88:91], v[84:87], v[2:17]
	ds_read_b128 v[76:79], v100 offset:16384
	ds_read_b128 v[80:83], v101
	ds_read_b128 v[84:87], v101 offset:4096
	ds_read_b128 v[88:91], v100 offset:20480
	s_waitcnt vmcnt(0) lgkmcnt(0)
	s_barrier
; #define TILE_MN(t, M0, N0) do { int pan_ = (t) / (mtiles * 8); if (pan_ >= npan) pan_ = npan - 1; const int pw_ = (pan_ == npan - 1) ? ntiles - 8 * pan_ : 8; const int loc_ = (t) - pan_ * mtiles * 8; \
;         M0 = (loc_ / pw_) * 128; N0 = (8 * pan_ + loc_ % pw_) * 128; } while (0)
; template <class Epi>
; DI void gemm_phase(const u16* __restrict__ A, const u16* __restrict__ B, int mtiles, int ntiles, char* lds, const Epi& epi) {
;     ...
;         for (int kt = 0; kt < 16; ++kt) {
;             if (kt + 1 < 16) GSTAGE((kt + 1) & 1, kt + 1, ga, gb);
;             const char* sa = lds + (kt & 1) * 32768; const char* sb = sa + 16384;
; #pragma unroll
;             for (int ks = 0; ks < 4; ++ks) {
;                 bf16x8 fw[2], fx[2];
; #pragma unroll
;                 for (int ct = 0; ct < 2; ++ct) fw[ct] = *(const bf16x8*)(sb + swz(wn * 64 + ct * 32 + r, 2 * ks + h));
; #pragma unroll
;                 for (int tt = 0; tt < 2; ++tt) fx[tt] = *(const bf16x8*)(sa + swz(wm * 64 + tt * 32 + r, 2 * ks + h));
; #pragma unroll
;                 for (int ct = 0; ct < 2; ++ct)
; #pragma unroll
;                     for (int tt = 0; tt < 2; ++tt) acc[ct][tt] = __builtin_amdgcn_mfma_f32_32x32x16_bf16(fw[ct], fx[tt], acc[ct][tt], 0, 0, 0);
;             }
;             __syncthreads();
;         }
;         const int nxt = tile + (int)gridDim.x; int m1 = 0, n1 = 0;
;         if (nxt < ntile) { TILE_MN(nxt, m1, n1); GSTAGE(0, 0, A + (size_t)m1 * 1024, B + (size_t)n1 * 1024); }
	v_mfma_f32_32x32x16_bf16 v[34:49], v[76:79], v[80:83], v[34:49]
	v_mfma_f32_32x32x16_bf16 v[18:33], v[76:79], v[84:87], v[18:33]
	v_mfma_f32_32x32x16_bf16 v[50:65], v[88:91], v[80:83], v[50:65]
	v_mfma_f32_32x32x16_bf16 v[2:17], v[88:91], v[84:87], v[2:17]
	ds_read_b128 v[76:79], v96 offset:32768
	ds_read_b128 v[80:83], v96 offset:36864
	ds_read_b128 v[84:87], v74 offset:49152
	ds_read_b128 v[88:91], v74 offset:53248
	s_waitcnt lgkmcnt(1)
	v_mfma_f32_32x32x16_bf16 v[34:49], v[84:87], v[76:79], v[34:49]
	v_mfma_f32_32x32x16_bf16 v[18:33], v[84:87], v[80:83], v[18:33]
	s_waitcnt lgkmcnt(0)
	v_mfma_f32_32x32x16_bf16 v[50:65], v[88:91], v[76:79], v[50:65]
	v_mfma_f32_32x32x16_bf16 v[2:17], v[88:91], v[80:83], v[2:17]
	ds_read_b128 v[76:79], v95 offset:49152
	ds_read_b128 v[80:83], v97 offset:32768
	ds_read_b128 v[84:87], v97 offset:36864
	ds_read_b128 v[88:91], v95 offset:53248
	s_waitcnt lgkmcnt(2)
	v_mfma_f32_32x32x16_bf16 v[34:49], v[76:79], v[80:83], v[34:49]
	s_waitcnt lgkmcnt(1)
	v_mfma_f32_32x32x16_bf16 v[18:33], v[76:79], v[84:87], v[18:33]
	s_waitcnt lgkmcnt(0)
	v_mfma_f32_32x32x16_bf16 v[50:65], v[88:91], v[80:83], v[50:65]
	v_mfma_f32_32x32x16_bf16 v[2:17], v[88:91], v[84:87], v[2:17]
	ds_read_b128 v[76:79], v98 offset:49152
	ds_read_b128 v[80:83], v99 offset:32768
	ds_read_b128 v[84:87], v99 offset:36864
	ds_read_b128 v[88:91], v98 offset:53248
	s_waitcnt lgkmcnt(2)
	v_mfma_f32_32x32x16_bf16 v[34:49], v[76:79], v[80:83], v[34:49]
	s_waitcnt lgkmcnt(1)
	v_mfma_f32_32x32x16_bf16 v[18:33], v[76:79], v[84:87], v[18:33]
	s_waitcnt lgkmcnt(0)
	v_mfma_f32_32x32x16_bf16 v[50:65], v[88:91], v[80:83], v[50:65]
	v_mfma_f32_32x32x16_bf16 v[2:17], v[88:91], v[84:87], v[2:17]
	ds_read_b128 v[76:79], v100 offset:49152
	ds_read_b128 v[80:83], v101 offset:32768
	ds_read_b128 v[84:87], v101 offset:36864
	ds_read_b128 v[88:91], v100 offset:53248
	s_waitcnt lgkmcnt(0)
	s_barrier
	v_mfma_f32_32x32x16_bf16 v[34:49], v[76:79], v[80:83], v[34:49]
	v_mfma_f32_32x32x16_bf16 v[18:33], v[76:79], v[84:87], v[18:33]
	v_mfma_f32_32x32x16_bf16 v[50:65], v[88:91], v[80:83], v[50:65]
	v_mfma_f32_32x32x16_bf16 v[2:17], v[88:91], v[84:87], v[2:17]
	s_cbranch_scc1 .LBB0_99
	s_mov_b32 m0, s1
	s_mul_hi_i32 s1, s33, 0x3e0f83e1
	s_lshr_b32 s86, s1, 31
	s_ashr_i32 s1, s1, 8
	s_add_i32 s1, s1, s86
	s_cmpk_lt_i32 s33, 0x1080
	s_cselect_b32 s1, s1, 3
	s_cmp_eq_u32 s1, 3
	s_cselect_b32 s87, 9, 8
	v_cvt_f32_ubyte0_e32 v74, s87
	v_rcp_iflag_f32_e32 v74, v74
	s_sub_i32 s91, 0, s87
	s_mul_i32 s86, s1, 0xfffffbe0
	s_add_i32 s88, s33, s86
	v_mul_f32_e32 v74, 0x4f7ffffe, v74
	v_cvt_u32_f32_e32 v74, v74
	s_abs_i32 s89, s88
	s_ashr_i32 s86, s88, 31
	v_readfirstlane_b32 s92, v74
	s_mul_i32 s91, s91, s92
	s_mul_hi_u32 s91, s92, s91
	s_add_i32 s92, s92, s91
	s_mul_hi_u32 s91, s89, s92
	s_mul_i32 s92, s91, s87
	s_sub_i32 s89, s89, s92
	s_add_i32 s92, s91, 1
	s_sub_i32 s93, s89, s87
	s_cmp_ge_u32 s89, s87
	s_cselect_b32 s91, s92, s91
	s_cselect_b32 s89, s93, s89
	s_add_i32 s92, s91, 1
	s_cmp_ge_u32 s89, s87
	s_cselect_b32 s89, s92, s91
	s_xor_b32 s89, s89, s86
	s_sub_i32 s89, s89, s86
	s_lshl_b32 s86, s89, 7
	s_mul_i32 s89, s89, s87
	s_sub_i32 s87, s88, s89
	s_lshl_b32 s1, s1, 10
	s_lshl_b32 s87, s87, 7
	s_add_i32 s88, s87, s1
	s_ashr_i32 s87, s86, 31
	s_lshl_b64 s[92:93], s[86:87], 11
	s_add_u32 s92, s54, s92
	s_addc_u32 s93, s55, s93
	s_ashr_i32 s89, s88, 31
	s_lshl_b64 s[94:95], s[88:89], 11
	v_readlane_b32 s1, v236, 9
	s_add_u32 s94, s1, s94
	v_readlane_b32 s1, v236, 11
	s_addc_u32 s95, s1, s95
	v_lshl_add_u64 v[76:77], s[92:93], 0, v[66:67]
	global_load_lds_dwordx4 v[76:77], off
	v_lshl_add_u64 v[66:67], s[94:95], 0, v[66:67]
	s_mov_b32 m0, s7
	s_nop 0
	global_load_lds_dwordx4 v[66:67], off
	v_lshl_add_u64 v[66:67], s[92:93], 0, v[68:69]
	s_mov_b32 m0, s38
	s_nop 0
	global_load_lds_dwordx4 v[66:67], off
	v_lshl_add_u64 v[66:67], s[94:95], 0, v[68:69]
	s_mov_b32 m0, s39
	s_nop 0
	global_load_lds_dwordx4 v[66:67], off
	v_lshl_add_u64 v[66:67], s[92:93], 0, v[70:71]
	s_mov_b32 m0, s50
	s_nop 0
	global_load_lds_dwordx4 v[66:67], off
	v_lshl_add_u64 v[66:67], s[94:95], 0, v[70:71]
	s_mov_b32 m0, s51
	s_nop 0
	global_load_lds_dwordx4 v[66:67], off
	v_lshl_add_u64 v[66:67], s[92:93], 0, v[72:73]
	s_mov_b32 m0, s83
	s_nop 0
	global_load_lds_dwordx4 v[66:67], off
	v_lshl_add_u64 v[66:67], s[94:95], 0, v[72:73]
	s_mov_b32 m0, s90
	s_nop 0
	global_load_lds_dwordx4 v[66:67], off

; DI float4 ntld4(const float* p) { const f32x4 v = __builtin_nontemporal_load((const f32x4*)p); return (float4){v[0], v[1], v[2], v[3]}; }
; DI void gemm_out(const Params& p, char* lds) {
;     ...
;     for (int tile = vb; tile < ntile; tile += gridDim.x) {
;         int tid = threadIdx.x; asm volatile("" : "+v"(tid));
;         const int lane = tid & 63, wave = __builtin_amdgcn_readfirstlane(tid >> 6); const int wn = wave >> 1, wm = wave & 1; const int q = lane & 15, g = lane >> 4;
;         const int mt = tile >> 3, nt = tile & 7; const int m0 = mt * 96, n0 = nt * 128;
;         f32x4 acc[4][3];
; #pragma unroll
;         for (int a = 0; a < 4; ++a)
; #pragma unroll
;             for (int b = 0; b < 3; ++b) acc[a][b] = (f32x4){0.f, 0.f, 0.f, 0.f};
;         unsigned soffb[4], soffa[3];
; #pragma unroll
;         for (int i = 0; i < 4; ++i) { const int row = 8 * (i * 4 + wave) + (lane >> 3); const int ch = (lane & 7) ^ ((row >> 1) & 7); soffb[i] = (unsigned)(row * 1024 + ch * 8); }
; #pragma unroll
;         for (int i = 0; i < 3; ++i) { const int row = 8 * (i * 4 + wave) + (lane >> 3); const int ch = (lane & 7) ^ ((row >> 1) & 7); soffa[i] = (unsigned)(row * 1024 + ch * 8); }
;         const u16* ga = A + (size_t)m0 * 1024; const u16* gb = B + (size_t)n0 * 1024;
;     ...
;         OSTAGE(0, 0);
;         float4 xres[3][4];
; #pragma unroll
;         for (int tt = 0; tt < 3; ++tt) { const int row = m0 + wm * 48 + tt * 16 + q; const float* xr = row < NTP ? p.x_p + (size_t)row * DM : p.x_s + (size_t)(row - NTP) * DM;
; #pragma unroll
;             for (int ct = 0; ct < 4; ++ct) xres[tt][ct] = ntld4(xr + n0 + wn * 64 + ct * 16 + 4 * g); }
;         __syncthreads();
;         for (int kt = 0; kt < 16; ++kt) {
;             if (kt + 1 < 16) OSTAGE((kt + 1) & 1, kt + 1);
.Lo_tile:
	v_mov_b32_e32 v18, v0
	s_ashr_i32 s83, s82, 31
	v_readfirstlane_b32 s1, v18
	s_ashr_i32 s7, s1, 6
	s_ashr_i32 s4, s1, 7
	s_and_b32 s6, s7, 1
	v_bfe_u32 v2, v18, 3, 3
	s_lshl_b64 s[38:39], s[82:83], 11
	v_lshl_or_b32 v2, s7, 3, v2
	s_add_u32 s38, s54, s38
	v_lshrrev_b32_e32 v3, 1, v2
	s_addc_u32 s39, s55, s39
	s_ashr_i32 s1, s0, 31
	v_xor_b32_e32 v3, v3, v18
	s_lshl_b64 s[50:51], s[0:1], 11
	v_readlane_b32 s1, v236, 9
	v_lshlrev_b32_e32 v2, 10, v2
	v_lshlrev_b32_e32 v3, 3, v3
	s_add_u32 s50, s1, s50
	v_readlane_b32 s1, v236, 11
	v_and_or_b32 v74, v3, 56, v2
	s_addc_u32 s51, s1, s51
	s_lshl_b32 s1, s7, 10
	v_lshlrev_b64 v[66:67], 1, v[74:75]
	s_add_i32 s1, s1, 0
	v_add_u32_e32 v2, 0x8000, v74
	v_bfe_u32 v93, v18, 5, 1
	v_lshrrev_b32_e32 v8, 1, v18
	v_mov_b32_e32 v3, v75
	v_lshl_add_u64 v[76:77], s[38:39], 0, v[66:67]
	s_add_i32 s86, s1, 0x8000
	v_bitop3_b32 v10, v93, v8, 7 bitop3:0x78
	v_lshl_add_u64 v[8:9], v[76:77], 0, s[8:9]
	s_mov_b32 m0, s86
	v_lshl_add_u64 v[78:79], s[50:51], 0, v[66:67]
	s_add_i32 s87, s1, 0xc000
	v_lshlrev_b64 v[68:69], 1, v[2:3]
	v_add_u32_e32 v4, 0x10000, v74
	s_waitcnt vmcnt(0) lgkmcnt(0)
	s_barrier
	v_mov_b32_e32 v5, v75
	global_load_lds_dwordx4 v[8:9], off
	v_lshl_add_u64 v[8:9], v[78:79], 0, s[8:9]
	s_mov_b32 m0, s87
	v_lshl_add_u64 v[80:81], s[38:39], 0, v[68:69]
	s_add_i32 s88, s1, 0x9000
	global_load_lds_dwordx4 v[8:9], off
	v_lshl_add_u64 v[2:3], v[80:81], 0, s[8:9]
	s_mov_b32 m0, s88
	v_lshl_add_u64 v[82:83], s[50:51], 0, v[68:69]
	s_add_i32 s89, s1, 0xd000
	v_lshlrev_b64 v[70:71], 1, v[4:5]
	v_add_u32_e32 v6, 0x18000, v74
	v_mov_b32_e32 v7, v75
	global_load_lds_dwordx4 v[2:3], off
	v_lshl_add_u64 v[2:3], v[82:83], 0, s[8:9]
	s_mov_b32 m0, s89
	v_lshl_add_u64 v[84:85], s[38:39], 0, v[70:71]
	s_add_i32 s91, s1, 0xa000
	global_load_lds_dwordx4 v[2:3], off
	v_lshl_add_u64 v[2:3], v[84:85], 0, s[8:9]
	s_mov_b32 m0, s91
	v_lshl_add_u64 v[86:87], s[50:51], 0, v[70:71]
	s_add_i32 s92, s1, 0xe000
	v_lshlrev_b64 v[72:73], 1, v[6:7]
	global_load_lds_dwordx4 v[2:3], off
	v_lshl_add_u64 v[2:3], v[86:87], 0, s[8:9]
	s_mov_b32 m0, s92
	v_lshl_add_u64 v[88:89], s[38:39], 0, v[72:73]
	s_add_i32 s93, s1, 0xb000
	v_and_b32_e32 v94, 31, v18
	global_load_lds_dwordx4 v[2:3], off
	v_lshl_add_u64 v[2:3], v[88:89], 0, s[8:9]
	s_mov_b32 m0, s93
	v_lshl_add_u64 v[90:91], s[50:51], 0, v[72:73]
	s_add_i32 s94, s1, 0xf000
	s_lshl_b32 s7, s4, 13
	v_lshlrev_b32_e32 v116, 7, v94
	global_load_lds_dwordx4 v[2:3], off
	v_lshl_add_u64 v[2:3], v[90:91], 0, s[8:9]
	s_mov_b32 m0, s94
	v_lshl_add_u32 v6, v10, 4, 0
	global_load_lds_dwordx4 v[2:3], off
	v_add3_u32 v74, v6, s7, v116
	ds_read_b128 v[2:5], v74 offset:16384
	s_lshl_b32 s38, s6, 13
	v_add3_u32 v96, v6, s38, v116
	v_bfe_u32 v117, v18, 1, 3
	ds_read_b128 v[6:9], v96
	ds_read_b128 v[10:13], v96 offset:4096
	ds_read_b128 v[14:17], v74 offset:20480
	v_bitop3_b32 v18, v93, v117, 2 bitop3:0x36
	v_lshl_add_u32 v18, v18, 4, 0
	v_add3_u32 v95, v18, s7, v116
	ds_read_b128 v[50:53], v95 offset:16384
	s_waitcnt lgkmcnt(0)
	v_mfma_f32_32x32x16_bf16 v[34:49], v[6:9], v[2:5], 0
	v_add3_u32 v97, v18, s38, v116
	ds_read_b128 v[98:101], v97
	ds_read_b128 v[102:105], v97 offset:4096
	ds_read_b128 v[106:109], v95 offset:20480
	s_mov_b32 m0, s1
	s_add_i32 s39, s1, 0x5000
	s_add_i32 s50, s1, 0x2000
	s_add_i32 s51, s1, 0x6000
	s_add_i32 s83, s1, 0x3000
	v_mfma_f32_32x32x16_bf16 v[18:33], v[10:13], v[2:5], 0
	s_add_i32 s90, s1, 0x7000
	s_add_i32 s33, s33, s95
	s_waitcnt lgkmcnt(0)
	v_mfma_f32_32x32x16_bf16 v[34:49], v[98:101], v[50:53], v[34:49]
	v_mfma_f32_32x32x16_bf16 v[18:33], v[102:105], v[50:53], v[18:33]
	v_mfma_f32_32x32x16_bf16 v[50:65], v[6:9], v[14:17], 0
	v_mfma_f32_32x32x16_bf16 v[2:17], v[10:13], v[14:17], 0
	v_mfma_f32_32x32x16_bf16 v[50:65], v[98:101], v[106:109], v[50:65]
	v_bitop3_b32 v98, v93, v117, 4 bitop3:0x36
	v_lshl_add_u32 v99, v98, 4, 0
	v_add3_u32 v98, v99, s7, v116
	v_add3_u32 v99, v99, s38, v116
	v_mfma_f32_32x32x16_bf16 v[2:17], v[102:105], v[106:109], v[2:17]
	ds_read_b128 v[100:103], v98 offset:16384
	ds_read_b128 v[104:107], v99
	ds_read_b128 v[108:111], v99 offset:4096
	ds_read_b128 v[112:115], v98 offset:20480
	s_waitcnt lgkmcnt(0)
	v_mfma_f32_32x32x16_bf16 v[34:49], v[104:107], v[100:103], v[34:49]
	v_mfma_f32_32x32x16_bf16 v[18:33], v[108:111], v[100:103], v[18:33]
	v_bitop3_b32 v100, v93, v117, 6 bitop3:0x36
	v_lshl_add_u32 v101, v100, 4, 0
	v_add3_u32 v100, v101, s7, v116
	v_add3_u32 v101, v101, s38, v116
	s_add_i32 s7, s1, 0x4000
	s_add_i32 s38, s1, 0x1000
	s_cmpk_gt_i32 s33, 0x41f
	v_mfma_f32_32x32x16_bf16 v[50:65], v[104:107], v[112:115], v[50:65]
	v_mfma_f32_32x32x16_bf16 v[2:17], v[108:111], v[112:115], v[2:17]
	ds_read_b128 v[238:241], v100 offset:16384
	ds_read_b128 v[242:245], v101
	ds_read_b128 v[246:249], v101 offset:4096
	ds_read_b128 v[250:253], v100 offset:20480
	s_waitcnt vmcnt(0) lgkmcnt(0)
	s_barrier
; DI void gemm_out(const Params& p, char* lds) {
;     ...
;         for (int kt = 0; kt < 16; ++kt) {
;             if (kt + 1 < 16) OSTAGE((kt + 1) & 1, kt + 1);
;             const char* sb = lds + (kt & 1) * 28672; const char* sa = sb + 16384;
; #pragma unroll
;             for (int ks = 0; ks < 2; ++ks) {
;                 bf16x8 fw[4], fx[3];
; #pragma unroll
;                 for (int ct = 0; ct < 4; ++ct) fw[ct] = *(const bf16x8*)(sb + swz(wn * 64 + ct * 16 + q, 4 * ks + g));
; #pragma unroll
;                 for (int tt = 0; tt < 3; ++tt) fx[tt] = *(const bf16x8*)(sa + swz(wm * 48 + tt * 16 + q, 4 * ks + g));
; #pragma unroll
;                 for (int ct = 0; ct < 4; ++ct)
; #pragma unroll
;                     for (int tt = 0; tt < 3; ++tt) acc[ct][tt] = __builtin_amdgcn_mfma_f32_16x16x32_bf16(fw[ct], fx[tt], acc[ct][tt], 0, 0, 0);
;             }
;             __syncthreads();
;         }
	ds_read_b128 v[102:105], v74 offset:49152
	ds_read_b128 v[106:109], v96 offset:32768
	ds_read_b128 v[110:113], v96 offset:36864
	ds_read_b128 v[114:117], v74 offset:53248
	v_mfma_f32_32x32x16_bf16 v[34:49], v[242:245], v[238:241], v[34:49]
	v_mfma_f32_32x32x16_bf16 v[18:33], v[246:249], v[238:241], v[18:33]
	v_lshl_add_u64 v[254:255], v[76:77], 0, s[10:11]
	global_load_lds_dwordx4 v[254:255], off
	v_lshl_add_u64 v[254:255], v[78:79], 0, s[10:11]
	s_mov_b32 m0, s7
	s_nop 0
	global_load_lds_dwordx4 v[254:255], off
	v_lshl_add_u64 v[254:255], v[80:81], 0, s[10:11]
	s_mov_b32 m0, s38
	v_mfma_f32_32x32x16_bf16 v[50:65], v[242:245], v[250:253], v[50:65]
	global_load_lds_dwordx4 v[254:255], off
	v_lshl_add_u64 v[254:255], v[82:83], 0, s[10:11]
	s_mov_b32 m0, s39
	s_nop 0
	global_load_lds_dwordx4 v[254:255], off
	v_lshl_add_u64 v[254:255], v[84:85], 0, s[10:11]
	s_mov_b32 m0, s50
	v_mfma_f32_32x32x16_bf16 v[2:17], v[246:249], v[250:253], v[2:17]
	global_load_lds_dwordx4 v[254:255], off
	s_waitcnt lgkmcnt(0)
	ds_read_b128 v[238:241], v95 offset:49152
	ds_read_b128 v[242:245], v97 offset:32768
	ds_read_b128 v[246:249], v97 offset:36864
	ds_read_b128 v[250:253], v95 offset:53248
	v_mfma_f32_32x32x16_bf16 v[34:49], v[106:109], v[102:105], v[34:49]
	v_lshl_add_u64 v[254:255], v[86:87], 0, s[10:11]
	s_mov_b32 m0, s51
	s_nop 0
	global_load_lds_dwordx4 v[254:255], off
	v_mfma_f32_32x32x16_bf16 v[18:33], v[110:113], v[102:105], v[18:33]
	v_lshl_add_u64 v[254:255], v[88:89], 0, s[10:11]
	s_mov_b32 m0, s83
	s_nop 0
	global_load_lds_dwordx4 v[254:255], off
	v_mfma_f32_32x32x16_bf16 v[50:65], v[106:109], v[114:117], v[50:65]
	v_lshl_add_u64 v[254:255], v[90:91], 0, s[10:11]
	s_mov_b32 m0, s90
	s_nop 0
	global_load_lds_dwordx4 v[254:255], off
	v_mfma_f32_32x32x16_bf16 v[2:17], v[110:113], v[114:117], v[2:17]
	s_mov_b32 m0, s86
	s_waitcnt lgkmcnt(0)
	ds_read_b128 v[102:105], v98 offset:49152
	ds_read_b128 v[106:109], v99 offset:32768
	ds_read_b128 v[110:113], v99 offset:36864
	ds_read_b128 v[114:117], v98 offset:53248
	v_mfma_f32_32x32x16_bf16 v[34:49], v[242:245], v[238:241], v[34:49]
	v_mfma_f32_32x32x16_bf16 v[18:33], v[246:249], v[238:241], v[18:33]
	v_mfma_f32_32x32x16_bf16 v[50:65], v[242:245], v[250:253], v[50:65]
	v_mfma_f32_32x32x16_bf16 v[2:17], v[246:249], v[250:253], v[2:17]
	s_waitcnt lgkmcnt(0)
	ds_read_b128 v[238:241], v100 offset:49152
	ds_read_b128 v[242:245], v101 offset:32768
	ds_read_b128 v[246:249], v101 offset:36864
	ds_read_b128 v[250:253], v100 offset:53248
	v_mfma_f32_32x32x16_bf16 v[34:49], v[106:109], v[102:105], v[34:49]
	v_mfma_f32_32x32x16_bf16 v[18:33], v[110:113], v[102:105], v[18:33]
	v_mfma_f32_32x32x16_bf16 v[50:65], v[106:109], v[114:117], v[50:65]
	v_mfma_f32_32x32x16_bf16 v[2:17], v[110:113], v[114:117], v[2:17]
	s_waitcnt vmcnt(0) lgkmcnt(0)
	s_barrier
	ds_read_b128 v[102:105], v74 offset:16384
	ds_read_b128 v[106:109], v96
	ds_read_b128 v[110:113], v96 offset:4096
	ds_read_b128 v[114:117], v74 offset:20480
	v_mfma_f32_32x32x16_bf16 v[34:49], v[242:245], v[238:241], v[34:49]
	v_mfma_f32_32x32x16_bf16 v[18:33], v[246:249], v[238:241], v[18:33]
	v_lshl_add_u64 v[254:255], v[76:77], 0, s[12:13]
	global_load_lds_dwordx4 v[254:255], off
	v_lshl_add_u64 v[254:255], v[78:79], 0, s[12:13]
	s_mov_b32 m0, s87
	s_nop 0
	global_load_lds_dwordx4 v[254:255], off
	v_lshl_add_u64 v[254:255], v[80:81], 0, s[12:13]
	s_mov_b32 m0, s88
	v_mfma_f32_32x32x16_bf16 v[50:65], v[242:245], v[250:253], v[50:65]
	global_load_lds_dwordx4 v[254:255], off
	v_lshl_add_u64 v[254:255], v[82:83], 0, s[12:13]
	s_mov_b32 m0, s89
	s_nop 0
	global_load_lds_dwordx4 v[254:255], off
	v_lshl_add_u64 v[254:255], v[84:85], 0, s[12:13]
	s_mov_b32 m0, s91
	v_mfma_f32_32x32x16_bf16 v[2:17], v[246:249], v[250:253], v[2:17]
	global_load_lds_dwordx4 v[254:255], off
	s_waitcnt lgkmcnt(0)
	ds_read_b128 v[238:241], v95 offset:16384
	ds_read_b128 v[242:245], v97
	ds_read_b128 v[246:249], v97 offset:4096
	ds_read_b128 v[250:253], v95 offset:20480
	v_mfma_f32_32x32x16_bf16 v[34:49], v[106:109], v[102:105], v[34:49]
	v_lshl_add_u64 v[254:255], v[86:87], 0, s[12:13]
	s_mov_b32 m0, s92
	s_nop 0
	global_load_lds_dwordx4 v[254:255], off
	v_mfma_f32_32x32x16_bf16 v[18:33], v[110:113], v[102:105], v[18:33]
	v_lshl_add_u64 v[254:255], v[88:89], 0, s[12:13]
	s_mov_b32 m0, s93
	s_nop 0
	global_load_lds_dwordx4 v[254:255], off
	v_mfma_f32_32x32x16_bf16 v[50:65], v[106:109], v[114:117], v[50:65]
	v_lshl_add_u64 v[254:255], v[90:91], 0, s[12:13]
	s_mov_b32 m0, s94
	s_nop 0
	global_load_lds_dwordx4 v[254:255], off
	v_mfma_f32_32x32x16_bf16 v[2:17], v[110:113], v[114:117], v[2:17]
	s_mov_b32 m0, s1
	s_waitcnt lgkmcnt(0)
	ds_read_b128 v[102:105], v98 offset:16384
	ds_read_b128 v[106:109], v99
	ds_read_b128 v[110:113], v99 offset:4096
	ds_read_b128 v[114:117], v98 offset:20480
	v_mfma_f32_32x32x16_bf16 v[34:49], v[242:245], v[238:241], v[34:49]
	v_mfma_f32_32x32x16_bf16 v[18:33], v[246:249], v[238:241], v[18:33]
	v_mfma_f32_32x32x16_bf16 v[50:65], v[242:245], v[250:253], v[50:65]
	v_mfma_f32_32x32x16_bf16 v[2:17], v[246:249], v[250:253], v[2:17]
	s_waitcnt lgkmcnt(0)
	ds_read_b128 v[238:241], v100 offset:16384
	ds_read_b128 v[242:245], v101
	ds_read_b128 v[246:249], v101 offset:4096
	ds_read_b128 v[250:253], v100 offset:20480
	v_mfma_f32_32x32x16_bf16 v[34:49], v[106:109], v[102:105], v[34:49]
	v_mfma_f32_32x32x16_bf16 v[18:33], v[110:113], v[102:105], v[18:33]
	v_mfma_f32_32x32x16_bf16 v[50:65], v[106:109], v[114:117], v[50:65]
	v_mfma_f32_32x32x16_bf16 v[2:17], v[110:113], v[114:117], v[2:17]
	s_waitcnt vmcnt(0) lgkmcnt(0)
	s_barrier
; DI void gemm_out(const Params& p, char* lds) {
;     ...
;         for (int kt = 0; kt < 16; ++kt) {
;             if (kt + 1 < 16) OSTAGE((kt + 1) & 1, kt + 1);
;             const char* sb = lds + (kt & 1) * 28672; const char* sa = sb + 16384;
; #pragma unroll
;             for (int ks = 0; ks < 2; ++ks) {
;                 bf16x8 fw[4], fx[3];
; #pragma unroll
;                 for (int ct = 0; ct < 4; ++ct) fw[ct] = *(const bf16x8*)(sb + swz(wn * 64 + ct * 16 + q, 4 * ks + g));
; #pragma unroll
;                 for (int tt = 0; tt < 3; ++tt) fx[tt] = *(const bf16x8*)(sa + swz(wm * 48 + tt * 16 + q, 4 * ks + g));
; #pragma unroll
;                 for (int ct = 0; ct < 4; ++ct)
; #pragma unroll
;                     for (int tt = 0; tt < 3; ++tt) acc[ct][tt] = __builtin_amdgcn_mfma_f32_16x16x32_bf16(fw[ct], fx[tt], acc[ct][tt], 0, 0, 0);
;             }
;             __syncthreads();
;         }
	ds_read_b128 v[102:105], v74 offset:49152
	ds_read_b128 v[106:109], v96 offset:32768
	ds_read_b128 v[110:113], v96 offset:36864
	ds_read_b128 v[114:117], v74 offset:53248
	v_mfma_f32_32x32x16_bf16 v[34:49], v[242:245], v[238:241], v[34:49]
	v_mfma_f32_32x32x16_bf16 v[18:33], v[246:249], v[238:241], v[18:33]
	v_lshl_add_u64 v[254:255], v[76:77], 0, s[14:15]
	global_load_lds_dwordx4 v[254:255], off
	v_lshl_add_u64 v[254:255], v[78:79], 0, s[14:15]
	s_mov_b32 m0, s7
	s_nop 0
	global_load_lds_dwordx4 v[254:255], off
	v_lshl_add_u64 v[254:255], v[80:81], 0, s[14:15]
	s_mov_b32 m0, s38
	v_mfma_f32_32x32x16_bf16 v[50:65], v[242:245], v[250:253], v[50:65]
	global_load_lds_dwordx4 v[254:255], off
	v_lshl_add_u64 v[254:255], v[82:83], 0, s[14:15]
	s_mov_b32 m0, s39
	s_nop 0
	global_load_lds_dwordx4 v[254:255], off
	v_lshl_add_u64 v[254:255], v[84:85], 0, s[14:15]
	s_mov_b32 m0, s50
	v_mfma_f32_32x32x16_bf16 v[2:17], v[246:249], v[250:253], v[2:17]
	global_load_lds_dwordx4 v[254:255], off
	s_waitcnt lgkmcnt(0)
	ds_read_b128 v[238:241], v95 offset:49152
	ds_read_b128 v[242:245], v97 offset:32768
	ds_read_b128 v[246:249], v97 offset:36864
	ds_read_b128 v[250:253], v95 offset:53248
	v_mfma_f32_32x32x16_bf16 v[34:49], v[106:109], v[102:105], v[34:49]
	v_lshl_add_u64 v[254:255], v[86:87], 0, s[14:15]
	s_mov_b32 m0, s51
	s_nop 0
	global_load_lds_dwordx4 v[254:255], off
	v_mfma_f32_32x32x16_bf16 v[18:33], v[110:113], v[102:105], v[18:33]
	v_lshl_add_u64 v[254:255], v[88:89], 0, s[14:15]
	s_mov_b32 m0, s83
	s_nop 0
	global_load_lds_dwordx4 v[254:255], off
	v_mfma_f32_32x32x16_bf16 v[50:65], v[106:109], v[114:117], v[50:65]
	v_lshl_add_u64 v[254:255], v[90:91], 0, s[14:15]
	s_mov_b32 m0, s90
	s_nop 0
	global_load_lds_dwordx4 v[254:255], off
	v_mfma_f32_32x32x16_bf16 v[2:17], v[110:113], v[114:117], v[2:17]
	s_mov_b32 m0, s86
	s_waitcnt lgkmcnt(0)
	ds_read_b128 v[102:105], v98 offset:49152
	ds_read_b128 v[106:109], v99 offset:32768
	ds_read_b128 v[110:113], v99 offset:36864
	ds_read_b128 v[114:117], v98 offset:53248
	v_mfma_f32_32x32x16_bf16 v[34:49], v[242:245], v[238:241], v[34:49]
	v_mfma_f32_32x32x16_bf16 v[18:33], v[246:249], v[238:241], v[18:33]
	v_mfma_f32_32x32x16_bf16 v[50:65], v[242:245], v[250:253], v[50:65]
	v_mfma_f32_32x32x16_bf16 v[2:17], v[246:249], v[250:253], v[2:17]
	s_waitcnt lgkmcnt(0)
	ds_read_b128 v[238:241], v100 offset:49152
	ds_read_b128 v[242:245], v101 offset:32768
	ds_read_b128 v[246:249], v101 offset:36864
	ds_read_b128 v[250:253], v100 offset:53248
	v_mfma_f32_32x32x16_bf16 v[34:49], v[106:109], v[102:105], v[34:49]
	v_mfma_f32_32x32x16_bf16 v[18:33], v[110:113], v[102:105], v[18:33]
	v_mfma_f32_32x32x16_bf16 v[50:65], v[106:109], v[114:117], v[50:65]
	v_mfma_f32_32x32x16_bf16 v[2:17], v[110:113], v[114:117], v[2:17]
	s_waitcnt vmcnt(0) lgkmcnt(0)
	s_barrier
	ds_read_b128 v[102:105], v74 offset:16384
	ds_read_b128 v[106:109], v96
	ds_read_b128 v[110:113], v96 offset:4096
	ds_read_b128 v[114:117], v74 offset:20480
	v_mfma_f32_32x32x16_bf16 v[34:49], v[242:245], v[238:241], v[34:49]
	v_mfma_f32_32x32x16_bf16 v[18:33], v[246:249], v[238:241], v[18:33]
	v_lshl_add_u64 v[254:255], v[76:77], 0, s[16:17]
	global_load_lds_dwordx4 v[254:255], off
	v_lshl_add_u64 v[254:255], v[78:79], 0, s[16:17]
	s_mov_b32 m0, s87
	s_nop 0
	global_load_lds_dwordx4 v[254:255], off
	v_lshl_add_u64 v[254:255], v[80:81], 0, s[16:17]
	s_mov_b32 m0, s88
	v_mfma_f32_32x32x16_bf16 v[50:65], v[242:245], v[250:253], v[50:65]
	global_load_lds_dwordx4 v[254:255], off
	v_lshl_add_u64 v[254:255], v[82:83], 0, s[16:17]
	s_mov_b32 m0, s89
	s_nop 0
	global_load_lds_dwordx4 v[254:255], off
	v_lshl_add_u64 v[254:255], v[84:85], 0, s[16:17]
	s_mov_b32 m0, s91
	v_mfma_f32_32x32x16_bf16 v[2:17], v[246:249], v[250:253], v[2:17]
	global_load_lds_dwordx4 v[254:255], off
	s_waitcnt lgkmcnt(0)
	ds_read_b128 v[238:241], v95 offset:16384
	ds_read_b128 v[242:245], v97
	ds_read_b128 v[246:249], v97 offset:4096
	ds_read_b128 v[250:253], v95 offset:20480
	v_mfma_f32_32x32x16_bf16 v[34:49], v[106:109], v[102:105], v[34:49]
	v_lshl_add_u64 v[254:255], v[86:87], 0, s[16:17]
	s_mov_b32 m0, s92
	s_nop 0
	global_load_lds_dwordx4 v[254:255], off
	v_mfma_f32_32x32x16_bf16 v[18:33], v[110:113], v[102:105], v[18:33]
	v_lshl_add_u64 v[254:255], v[88:89], 0, s[16:17]
	s_mov_b32 m0, s93
	s_nop 0
	global_load_lds_dwordx4 v[254:255], off
	v_mfma_f32_32x32x16_bf16 v[50:65], v[106:109], v[114:117], v[50:65]
	v_lshl_add_u64 v[254:255], v[90:91], 0, s[16:17]
	s_mov_b32 m0, s94
	s_nop 0
	global_load_lds_dwordx4 v[254:255], off
	v_mfma_f32_32x32x16_bf16 v[2:17], v[110:113], v[114:117], v[2:17]
	s_mov_b32 m0, s1
	s_waitcnt lgkmcnt(0)
	ds_read_b128 v[102:105], v98 offset:16384
	ds_read_b128 v[106:109], v99
	ds_read_b128 v[110:113], v99 offset:4096
	ds_read_b128 v[114:117], v98 offset:20480
	v_mfma_f32_32x32x16_bf16 v[34:49], v[242:245], v[238:241], v[34:49]
	v_mfma_f32_32x32x16_bf16 v[18:33], v[246:249], v[238:241], v[18:33]
	v_mfma_f32_32x32x16_bf16 v[50:65], v[242:245], v[250:253], v[50:65]
	v_mfma_f32_32x32x16_bf16 v[2:17], v[246:249], v[250:253], v[2:17]
	s_waitcnt lgkmcnt(0)
	ds_read_b128 v[238:241], v100 offset:16384
	ds_read_b128 v[242:245], v101
	ds_read_b128 v[246:249], v101 offset:4096
	ds_read_b128 v[250:253], v100 offset:20480
	v_mfma_f32_32x32x16_bf16 v[34:49], v[106:109], v[102:105], v[34:49]
	v_mfma_f32_32x32x16_bf16 v[18:33], v[110:113], v[102:105], v[18:33]
	v_mfma_f32_32x32x16_bf16 v[50:65], v[106:109], v[114:117], v[50:65]
	v_mfma_f32_32x32x16_bf16 v[2:17], v[110:113], v[114:117], v[2:17]
	s_waitcnt vmcnt(0) lgkmcnt(0)
	s_barrier
; DI void gemm_out(const Params& p, char* lds) {
;     ...
;         for (int kt = 0; kt < 16; ++kt) {
;             if (kt + 1 < 16) OSTAGE((kt + 1) & 1, kt + 1);
;             const char* sb = lds + (kt & 1) * 28672; const char* sa = sb + 16384;
; #pragma unroll
;             for (int ks = 0; ks < 2; ++ks) {
;                 bf16x8 fw[4], fx[3];
; #pragma unroll
;                 for (int ct = 0; ct < 4; ++ct) fw[ct] = *(const bf16x8*)(sb + swz(wn * 64 + ct * 16 + q, 4 * ks + g));
; #pragma unroll
;                 for (int tt = 0; tt < 3; ++tt) fx[tt] = *(const bf16x8*)(sa + swz(wm * 48 + tt * 16 + q, 4 * ks + g));
; #pragma unroll
;                 for (int ct = 0; ct < 4; ++ct)
; #pragma unroll
;                     for (int tt = 0; tt < 3; ++tt) acc[ct][tt] = __builtin_amdgcn_mfma_f32_16x16x32_bf16(fw[ct], fx[tt], acc[ct][tt], 0, 0, 0);
;             }
;             __syncthreads();
;         }
	ds_read_b128 v[102:105], v74 offset:49152
	ds_read_b128 v[106:109], v96 offset:32768
	ds_read_b128 v[110:113], v96 offset:36864
	ds_read_b128 v[114:117], v74 offset:53248
	v_mfma_f32_32x32x16_bf16 v[34:49], v[242:245], v[238:241], v[34:49]
	v_mfma_f32_32x32x16_bf16 v[18:33], v[246:249], v[238:241], v[18:33]
	v_lshl_add_u64 v[254:255], v[76:77], 0, s[18:19]
	global_load_lds_dwordx4 v[254:255], off
	v_lshl_add_u64 v[254:255], v[78:79], 0, s[18:19]
	s_mov_b32 m0, s7
	s_nop 0
	global_load_lds_dwordx4 v[254:255], off
	v_lshl_add_u64 v[254:255], v[80:81], 0, s[18:19]
	s_mov_b32 m0, s38
	v_mfma_f32_32x32x16_bf16 v[50:65], v[242:245], v[250:253], v[50:65]
	global_load_lds_dwordx4 v[254:255], off
	v_lshl_add_u64 v[254:255], v[82:83], 0, s[18:19]
	s_mov_b32 m0, s39
	s_nop 0
	global_load_lds_dwordx4 v[254:255], off
	v_lshl_add_u64 v[254:255], v[84:85], 0, s[18:19]
	s_mov_b32 m0, s50
	v_mfma_f32_32x32x16_bf16 v[2:17], v[246:249], v[250:253], v[2:17]
	global_load_lds_dwordx4 v[254:255], off
	s_waitcnt lgkmcnt(0)
	ds_read_b128 v[238:241], v95 offset:49152
	ds_read_b128 v[242:245], v97 offset:32768
	ds_read_b128 v[246:249], v97 offset:36864
	ds_read_b128 v[250:253], v95 offset:53248
	v_mfma_f32_32x32x16_bf16 v[34:49], v[106:109], v[102:105], v[34:49]
	v_lshl_add_u64 v[254:255], v[86:87], 0, s[18:19]
	s_mov_b32 m0, s51
	s_nop 0
	global_load_lds_dwordx4 v[254:255], off
	v_mfma_f32_32x32x16_bf16 v[18:33], v[110:113], v[102:105], v[18:33]
	v_lshl_add_u64 v[254:255], v[88:89], 0, s[18:19]
	s_mov_b32 m0, s83
	s_nop 0
	global_load_lds_dwordx4 v[254:255], off
	v_mfma_f32_32x32x16_bf16 v[50:65], v[106:109], v[114:117], v[50:65]
	v_lshl_add_u64 v[254:255], v[90:91], 0, s[18:19]
	s_mov_b32 m0, s90
	s_nop 0
	global_load_lds_dwordx4 v[254:255], off
	v_mfma_f32_32x32x16_bf16 v[2:17], v[110:113], v[114:117], v[2:17]
	s_mov_b32 m0, s86
	s_waitcnt lgkmcnt(0)
	ds_read_b128 v[102:105], v98 offset:49152
	ds_read_b128 v[106:109], v99 offset:32768
	ds_read_b128 v[110:113], v99 offset:36864
	ds_read_b128 v[114:117], v98 offset:53248
	v_mfma_f32_32x32x16_bf16 v[34:49], v[242:245], v[238:241], v[34:49]
	v_mfma_f32_32x32x16_bf16 v[18:33], v[246:249], v[238:241], v[18:33]
	v_mfma_f32_32x32x16_bf16 v[50:65], v[242:245], v[250:253], v[50:65]
	v_mfma_f32_32x32x16_bf16 v[2:17], v[246:249], v[250:253], v[2:17]
	s_waitcnt lgkmcnt(0)
	ds_read_b128 v[238:241], v100 offset:49152
	ds_read_b128 v[242:245], v101 offset:32768
	ds_read_b128 v[246:249], v101 offset:36864
	ds_read_b128 v[250:253], v100 offset:53248
	v_mfma_f32_32x32x16_bf16 v[34:49], v[106:109], v[102:105], v[34:49]
	v_mfma_f32_32x32x16_bf16 v[18:33], v[110:113], v[102:105], v[18:33]
	v_mfma_f32_32x32x16_bf16 v[50:65], v[106:109], v[114:117], v[50:65]
	v_mfma_f32_32x32x16_bf16 v[2:17], v[110:113], v[114:117], v[2:17]
	s_waitcnt vmcnt(0) lgkmcnt(0)
	s_barrier
	ds_read_b128 v[102:105], v74 offset:16384
	ds_read_b128 v[106:109], v96
	ds_read_b128 v[110:113], v96 offset:4096
	ds_read_b128 v[114:117], v74 offset:20480
	v_mfma_f32_32x32x16_bf16 v[34:49], v[242:245], v[238:241], v[34:49]
	v_mfma_f32_32x32x16_bf16 v[18:33], v[246:249], v[238:241], v[18:33]
	v_lshl_add_u64 v[254:255], v[76:77], 0, s[20:21]
	global_load_lds_dwordx4 v[254:255], off
	v_lshl_add_u64 v[254:255], v[78:79], 0, s[20:21]
	s_mov_b32 m0, s87
	s_nop 0
	global_load_lds_dwordx4 v[254:255], off
	v_lshl_add_u64 v[254:255], v[80:81], 0, s[20:21]
	s_mov_b32 m0, s88
	v_mfma_f32_32x32x16_bf16 v[50:65], v[242:245], v[250:253], v[50:65]
	global_load_lds_dwordx4 v[254:255], off
	v_lshl_add_u64 v[254:255], v[82:83], 0, s[20:21]
	s_mov_b32 m0, s89
	s_nop 0
	global_load_lds_dwordx4 v[254:255], off
	v_lshl_add_u64 v[254:255], v[84:85], 0, s[20:21]
	s_mov_b32 m0, s91
	v_mfma_f32_32x32x16_bf16 v[2:17], v[246:249], v[250:253], v[2:17]
	global_load_lds_dwordx4 v[254:255], off
	s_waitcnt lgkmcnt(0)
	ds_read_b128 v[238:241], v95 offset:16384
	ds_read_b128 v[242:245], v97
	ds_read_b128 v[246:249], v97 offset:4096
	ds_read_b128 v[250:253], v95 offset:20480
	v_mfma_f32_32x32x16_bf16 v[34:49], v[106:109], v[102:105], v[34:49]
	v_lshl_add_u64 v[254:255], v[86:87], 0, s[20:21]
	s_mov_b32 m0, s92
	s_nop 0
	global_load_lds_dwordx4 v[254:255], off
	v_mfma_f32_32x32x16_bf16 v[18:33], v[110:113], v[102:105], v[18:33]
	v_lshl_add_u64 v[254:255], v[88:89], 0, s[20:21]
	s_mov_b32 m0, s93
	s_nop 0
	global_load_lds_dwordx4 v[254:255], off
	v_mfma_f32_32x32x16_bf16 v[50:65], v[106:109], v[114:117], v[50:65]
	v_lshl_add_u64 v[254:255], v[90:91], 0, s[20:21]
	s_mov_b32 m0, s94
	s_nop 0
	global_load_lds_dwordx4 v[254:255], off
	v_mfma_f32_32x32x16_bf16 v[2:17], v[110:113], v[114:117], v[2:17]
	s_mov_b32 m0, s1
	s_waitcnt lgkmcnt(0)
	ds_read_b128 v[102:105], v98 offset:16384
	ds_read_b128 v[106:109], v99
	ds_read_b128 v[110:113], v99 offset:4096
	ds_read_b128 v[114:117], v98 offset:20480
	v_mfma_f32_32x32x16_bf16 v[34:49], v[242:245], v[238:241], v[34:49]
	v_mfma_f32_32x32x16_bf16 v[18:33], v[246:249], v[238:241], v[18:33]
	v_mfma_f32_32x32x16_bf16 v[50:65], v[242:245], v[250:253], v[50:65]
	v_mfma_f32_32x32x16_bf16 v[2:17], v[246:249], v[250:253], v[2:17]
	s_waitcnt lgkmcnt(0)
	ds_read_b128 v[238:241], v100 offset:16384
	ds_read_b128 v[242:245], v101
	ds_read_b128 v[246:249], v101 offset:4096
	ds_read_b128 v[250:253], v100 offset:20480
	v_mfma_f32_32x32x16_bf16 v[34:49], v[106:109], v[102:105], v[34:49]
	v_mfma_f32_32x32x16_bf16 v[18:33], v[110:113], v[102:105], v[18:33]
	v_mfma_f32_32x32x16_bf16 v[50:65], v[106:109], v[114:117], v[50:65]
	v_mfma_f32_32x32x16_bf16 v[2:17], v[110:113], v[114:117], v[2:17]
	s_waitcnt vmcnt(0) lgkmcnt(0)
	s_barrier
; DI void gemm_out(const Params& p, char* lds) {
;     ...
;         for (int kt = 0; kt < 16; ++kt) {
;             if (kt + 1 < 16) OSTAGE((kt + 1) & 1, kt + 1);
;             const char* sb = lds + (kt & 1) * 28672; const char* sa = sb + 16384;
; #pragma unroll
;             for (int ks = 0; ks < 2; ++ks) {
;                 bf16x8 fw[4], fx[3];
; #pragma unroll
;                 for (int ct = 0; ct < 4; ++ct) fw[ct] = *(const bf16x8*)(sb + swz(wn * 64 + ct * 16 + q, 4 * ks + g));
; #pragma unroll
;                 for (int tt = 0; tt < 3; ++tt) fx[tt] = *(const bf16x8*)(sa + swz(wm * 48 + tt * 16 + q, 4 * ks + g));
; #pragma unroll
;                 for (int ct = 0; ct < 4; ++ct)
; #pragma unroll
;                     for (int tt = 0; tt < 3; ++tt) acc[ct][tt] = __builtin_amdgcn_mfma_f32_16x16x32_bf16(fw[ct], fx[tt], acc[ct][tt], 0, 0, 0);
;             }
;             __syncthreads();
;         }
	ds_read_b128 v[102:105], v74 offset:49152
	ds_read_b128 v[106:109], v96 offset:32768
	ds_read_b128 v[110:113], v96 offset:36864
	ds_read_b128 v[114:117], v74 offset:53248
	v_mfma_f32_32x32x16_bf16 v[34:49], v[242:245], v[238:241], v[34:49]
	v_mfma_f32_32x32x16_bf16 v[18:33], v[246:249], v[238:241], v[18:33]
	v_lshl_add_u64 v[254:255], v[76:77], 0, s[22:23]
	global_load_lds_dwordx4 v[254:255], off
	v_lshl_add_u64 v[254:255], v[78:79], 0, s[22:23]
	s_mov_b32 m0, s7
	s_nop 0
	global_load_lds_dwordx4 v[254:255], off
	v_lshl_add_u64 v[254:255], v[80:81], 0, s[22:23]
	s_mov_b32 m0, s38
	v_mfma_f32_32x32x16_bf16 v[50:65], v[242:245], v[250:253], v[50:65]
	global_load_lds_dwordx4 v[254:255], off
	v_lshl_add_u64 v[254:255], v[82:83], 0, s[22:23]
	s_mov_b32 m0, s39
	s_nop 0
	global_load_lds_dwordx4 v[254:255], off
	v_lshl_add_u64 v[254:255], v[84:85], 0, s[22:23]
	s_mov_b32 m0, s50
	v_mfma_f32_32x32x16_bf16 v[2:17], v[246:249], v[250:253], v[2:17]
	global_load_lds_dwordx4 v[254:255], off
	s_waitcnt lgkmcnt(0)
	ds_read_b128 v[238:241], v95 offset:49152
	ds_read_b128 v[242:245], v97 offset:32768
	ds_read_b128 v[246:249], v97 offset:36864
	ds_read_b128 v[250:253], v95 offset:53248
	v_mfma_f32_32x32x16_bf16 v[34:49], v[106:109], v[102:105], v[34:49]
	v_lshl_add_u64 v[254:255], v[86:87], 0, s[22:23]
	s_mov_b32 m0, s51
	s_nop 0
	global_load_lds_dwordx4 v[254:255], off
	v_mfma_f32_32x32x16_bf16 v[18:33], v[110:113], v[102:105], v[18:33]
	v_lshl_add_u64 v[254:255], v[88:89], 0, s[22:23]
	s_mov_b32 m0, s83
	s_nop 0
	global_load_lds_dwordx4 v[254:255], off
	v_mfma_f32_32x32x16_bf16 v[50:65], v[106:109], v[114:117], v[50:65]
	v_lshl_add_u64 v[254:255], v[90:91], 0, s[22:23]
	s_mov_b32 m0, s90
	s_nop 0
	global_load_lds_dwordx4 v[254:255], off
	v_mfma_f32_32x32x16_bf16 v[2:17], v[110:113], v[114:117], v[2:17]
	s_mov_b32 m0, s86
	s_waitcnt lgkmcnt(0)
	ds_read_b128 v[102:105], v98 offset:49152
	ds_read_b128 v[106:109], v99 offset:32768
	ds_read_b128 v[110:113], v99 offset:36864
	ds_read_b128 v[114:117], v98 offset:53248
	v_mfma_f32_32x32x16_bf16 v[34:49], v[242:245], v[238:241], v[34:49]
	v_mfma_f32_32x32x16_bf16 v[18:33], v[246:249], v[238:241], v[18:33]
	v_mfma_f32_32x32x16_bf16 v[50:65], v[242:245], v[250:253], v[50:65]
	v_mfma_f32_32x32x16_bf16 v[2:17], v[246:249], v[250:253], v[2:17]
	s_waitcnt lgkmcnt(0)
	ds_read_b128 v[238:241], v100 offset:49152
	ds_read_b128 v[242:245], v101 offset:32768
	ds_read_b128 v[246:249], v101 offset:36864
	ds_read_b128 v[250:253], v100 offset:53248
	v_mfma_f32_32x32x16_bf16 v[34:49], v[106:109], v[102:105], v[34:49]
	v_mfma_f32_32x32x16_bf16 v[18:33], v[110:113], v[102:105], v[18:33]
	v_mfma_f32_32x32x16_bf16 v[50:65], v[106:109], v[114:117], v[50:65]
	v_mfma_f32_32x32x16_bf16 v[2:17], v[110:113], v[114:117], v[2:17]
	s_waitcnt vmcnt(0) lgkmcnt(0)
	s_barrier
	ds_read_b128 v[102:105], v74 offset:16384
	ds_read_b128 v[106:109], v96
	ds_read_b128 v[110:113], v96 offset:4096
	ds_read_b128 v[114:117], v74 offset:20480
	v_mfma_f32_32x32x16_bf16 v[34:49], v[242:245], v[238:241], v[34:49]
	v_mfma_f32_32x32x16_bf16 v[18:33], v[246:249], v[238:241], v[18:33]
	v_lshl_add_u64 v[254:255], v[76:77], 0, s[24:25]
	global_load_lds_dwordx4 v[254:255], off
	v_lshl_add_u64 v[254:255], v[78:79], 0, s[24:25]
	s_mov_b32 m0, s87
	s_nop 0
	global_load_lds_dwordx4 v[254:255], off
	v_lshl_add_u64 v[254:255], v[80:81], 0, s[24:25]
	s_mov_b32 m0, s88
	v_mfma_f32_32x32x16_bf16 v[50:65], v[242:245], v[250:253], v[50:65]
	global_load_lds_dwordx4 v[254:255], off
	v_lshl_add_u64 v[254:255], v[82:83], 0, s[24:25]
	s_mov_b32 m0, s89
	s_nop 0
	global_load_lds_dwordx4 v[254:255], off
	v_lshl_add_u64 v[254:255], v[84:85], 0, s[24:25]
	s_mov_b32 m0, s91
	v_mfma_f32_32x32x16_bf16 v[2:17], v[246:249], v[250:253], v[2:17]
	global_load_lds_dwordx4 v[254:255], off
	s_waitcnt lgkmcnt(0)
	ds_read_b128 v[238:241], v95 offset:16384
	ds_read_b128 v[242:245], v97
	ds_read_b128 v[246:249], v97 offset:4096
	ds_read_b128 v[250:253], v95 offset:20480
	v_mfma_f32_32x32x16_bf16 v[34:49], v[106:109], v[102:105], v[34:49]
	v_lshl_add_u64 v[254:255], v[86:87], 0, s[24:25]
	s_mov_b32 m0, s92
	s_nop 0
	global_load_lds_dwordx4 v[254:255], off
	v_mfma_f32_32x32x16_bf16 v[18:33], v[110:113], v[102:105], v[18:33]
	v_lshl_add_u64 v[254:255], v[88:89], 0, s[24:25]
	s_mov_b32 m0, s93
	s_nop 0
	global_load_lds_dwordx4 v[254:255], off
	v_mfma_f32_32x32x16_bf16 v[50:65], v[106:109], v[114:117], v[50:65]
	v_lshl_add_u64 v[254:255], v[90:91], 0, s[24:25]
	s_mov_b32 m0, s94
	s_nop 0
	global_load_lds_dwordx4 v[254:255], off
	v_mfma_f32_32x32x16_bf16 v[2:17], v[110:113], v[114:117], v[2:17]
	s_mov_b32 m0, s1
	s_waitcnt lgkmcnt(0)
	ds_read_b128 v[102:105], v98 offset:16384
	ds_read_b128 v[106:109], v99
	ds_read_b128 v[110:113], v99 offset:4096
	ds_read_b128 v[114:117], v98 offset:20480
	v_mfma_f32_32x32x16_bf16 v[34:49], v[242:245], v[238:241], v[34:49]
	v_mfma_f32_32x32x16_bf16 v[18:33], v[246:249], v[238:241], v[18:33]
	v_mfma_f32_32x32x16_bf16 v[50:65], v[242:245], v[250:253], v[50:65]
	v_mfma_f32_32x32x16_bf16 v[2:17], v[246:249], v[250:253], v[2:17]
	s_waitcnt lgkmcnt(0)
	ds_read_b128 v[238:241], v100 offset:16384
	ds_read_b128 v[242:245], v101
	ds_read_b128 v[246:249], v101 offset:4096
	ds_read_b128 v[250:253], v100 offset:20480
	v_mfma_f32_32x32x16_bf16 v[34:49], v[106:109], v[102:105], v[34:49]
	v_mfma_f32_32x32x16_bf16 v[18:33], v[110:113], v[102:105], v[18:33]
	v_mfma_f32_32x32x16_bf16 v[50:65], v[106:109], v[114:117], v[50:65]
	v_mfma_f32_32x32x16_bf16 v[2:17], v[110:113], v[114:117], v[2:17]
	s_waitcnt vmcnt(0) lgkmcnt(0)
	s_barrier
; DI void gemm_out(const Params& p, char* lds) {
;     ...
;         for (int kt = 0; kt < 16; ++kt) {
;             if (kt + 1 < 16) OSTAGE((kt + 1) & 1, kt + 1);
;             const char* sb = lds + (kt & 1) * 28672; const char* sa = sb + 16384;
; #pragma unroll
;             for (int ks = 0; ks < 2; ++ks) {
;                 bf16x8 fw[4], fx[3];
; #pragma unroll
;                 for (int ct = 0; ct < 4; ++ct) fw[ct] = *(const bf16x8*)(sb + swz(wn * 64 + ct * 16 + q, 4 * ks + g));
; #pragma unroll
;                 for (int tt = 0; tt < 3; ++tt) fx[tt] = *(const bf16x8*)(sa + swz(wm * 48 + tt * 16 + q, 4 * ks + g));
; #pragma unroll
;                 for (int ct = 0; ct < 4; ++ct)
; #pragma unroll
;                     for (int tt = 0; tt < 3; ++tt) acc[ct][tt] = __builtin_amdgcn_mfma_f32_16x16x32_bf16(fw[ct], fx[tt], acc[ct][tt], 0, 0, 0);
;             }
;             __syncthreads();
;         }
	ds_read_b128 v[102:105], v74 offset:49152
	ds_read_b128 v[106:109], v96 offset:32768
	ds_read_b128 v[110:113], v96 offset:36864
	ds_read_b128 v[114:117], v74 offset:53248
	v_mfma_f32_32x32x16_bf16 v[34:49], v[242:245], v[238:241], v[34:49]
	v_mfma_f32_32x32x16_bf16 v[18:33], v[246:249], v[238:241], v[18:33]
	v_lshl_add_u64 v[254:255], v[76:77], 0, s[26:27]
	global_load_lds_dwordx4 v[254:255], off
	v_lshl_add_u64 v[254:255], v[78:79], 0, s[26:27]
	s_mov_b32 m0, s7
	s_nop 0
	global_load_lds_dwordx4 v[254:255], off
	v_lshl_add_u64 v[254:255], v[80:81], 0, s[26:27]
	s_mov_b32 m0, s38
	v_mfma_f32_32x32x16_bf16 v[50:65], v[242:245], v[250:253], v[50:65]
	global_load_lds_dwordx4 v[254:255], off
	v_lshl_add_u64 v[254:255], v[82:83], 0, s[26:27]
	s_mov_b32 m0, s39
	s_nop 0
	global_load_lds_dwordx4 v[254:255], off
	v_lshl_add_u64 v[254:255], v[84:85], 0, s[26:27]
	s_mov_b32 m0, s50
	v_mfma_f32_32x32x16_bf16 v[2:17], v[246:249], v[250:253], v[2:17]
	global_load_lds_dwordx4 v[254:255], off
	s_waitcnt lgkmcnt(0)
	ds_read_b128 v[238:241], v95 offset:49152
	ds_read_b128 v[242:245], v97 offset:32768
	ds_read_b128 v[246:249], v97 offset:36864
	ds_read_b128 v[250:253], v95 offset:53248
	v_mfma_f32_32x32x16_bf16 v[34:49], v[106:109], v[102:105], v[34:49]
	v_lshl_add_u64 v[254:255], v[86:87], 0, s[26:27]
	s_mov_b32 m0, s51
	s_nop 0
	global_load_lds_dwordx4 v[254:255], off
	v_mfma_f32_32x32x16_bf16 v[18:33], v[110:113], v[102:105], v[18:33]
	v_lshl_add_u64 v[254:255], v[88:89], 0, s[26:27]
	s_mov_b32 m0, s83
	s_nop 0
	global_load_lds_dwordx4 v[254:255], off
	v_mfma_f32_32x32x16_bf16 v[50:65], v[106:109], v[114:117], v[50:65]
	v_lshl_add_u64 v[254:255], v[90:91], 0, s[26:27]
	s_mov_b32 m0, s90
	s_nop 0
	global_load_lds_dwordx4 v[254:255], off
	v_mfma_f32_32x32x16_bf16 v[2:17], v[110:113], v[114:117], v[2:17]
	s_mov_b32 m0, s86
	s_waitcnt lgkmcnt(0)
	ds_read_b128 v[102:105], v98 offset:49152
	ds_read_b128 v[106:109], v99 offset:32768
	ds_read_b128 v[110:113], v99 offset:36864
	ds_read_b128 v[114:117], v98 offset:53248
	v_mfma_f32_32x32x16_bf16 v[34:49], v[242:245], v[238:241], v[34:49]
	v_mfma_f32_32x32x16_bf16 v[18:33], v[246:249], v[238:241], v[18:33]
	v_mfma_f32_32x32x16_bf16 v[50:65], v[242:245], v[250:253], v[50:65]
	v_mfma_f32_32x32x16_bf16 v[2:17], v[246:249], v[250:253], v[2:17]
	s_waitcnt lgkmcnt(0)
	ds_read_b128 v[238:241], v100 offset:49152
	ds_read_b128 v[242:245], v101 offset:32768
	ds_read_b128 v[246:249], v101 offset:36864
	ds_read_b128 v[250:253], v100 offset:53248
	v_mfma_f32_32x32x16_bf16 v[34:49], v[106:109], v[102:105], v[34:49]
	v_mfma_f32_32x32x16_bf16 v[18:33], v[110:113], v[102:105], v[18:33]
	v_mfma_f32_32x32x16_bf16 v[50:65], v[106:109], v[114:117], v[50:65]
	v_mfma_f32_32x32x16_bf16 v[2:17], v[110:113], v[114:117], v[2:17]
	s_waitcnt vmcnt(0) lgkmcnt(0)
	s_barrier
	ds_read_b128 v[102:105], v74 offset:16384
	ds_read_b128 v[106:109], v96
	ds_read_b128 v[110:113], v96 offset:4096
	ds_read_b128 v[114:117], v74 offset:20480
	v_mfma_f32_32x32x16_bf16 v[34:49], v[242:245], v[238:241], v[34:49]
	v_mfma_f32_32x32x16_bf16 v[18:33], v[246:249], v[238:241], v[18:33]
	v_lshl_add_u64 v[254:255], v[76:77], 0, s[28:29]
	global_load_lds_dwordx4 v[254:255], off
	v_lshl_add_u64 v[254:255], v[78:79], 0, s[28:29]
	s_mov_b32 m0, s87
	s_nop 0
	global_load_lds_dwordx4 v[254:255], off
	v_lshl_add_u64 v[254:255], v[80:81], 0, s[28:29]
	s_mov_b32 m0, s88
	v_mfma_f32_32x32x16_bf16 v[50:65], v[242:245], v[250:253], v[50:65]
	global_load_lds_dwordx4 v[254:255], off
	v_lshl_add_u64 v[254:255], v[82:83], 0, s[28:29]
	s_mov_b32 m0, s89
	s_nop 0
	global_load_lds_dwordx4 v[254:255], off
	v_lshl_add_u64 v[254:255], v[84:85], 0, s[28:29]
	s_mov_b32 m0, s91
	v_mfma_f32_32x32x16_bf16 v[2:17], v[246:249], v[250:253], v[2:17]
	global_load_lds_dwordx4 v[254:255], off
	s_waitcnt lgkmcnt(0)
	ds_read_b128 v[238:241], v95 offset:16384
	ds_read_b128 v[242:245], v97
	ds_read_b128 v[246:249], v97 offset:4096
	ds_read_b128 v[250:253], v95 offset:20480
	v_mfma_f32_32x32x16_bf16 v[34:49], v[106:109], v[102:105], v[34:49]
	v_lshl_add_u64 v[254:255], v[86:87], 0, s[28:29]
	s_mov_b32 m0, s92
	s_nop 0
	global_load_lds_dwordx4 v[254:255], off
	v_mfma_f32_32x32x16_bf16 v[18:33], v[110:113], v[102:105], v[18:33]
	v_lshl_add_u64 v[254:255], v[88:89], 0, s[28:29]
	s_mov_b32 m0, s93
	s_nop 0
	global_load_lds_dwordx4 v[254:255], off
	v_mfma_f32_32x32x16_bf16 v[50:65], v[106:109], v[114:117], v[50:65]
	v_lshl_add_u64 v[254:255], v[90:91], 0, s[28:29]
	s_mov_b32 m0, s94
	s_nop 0
	global_load_lds_dwordx4 v[254:255], off
	v_mfma_f32_32x32x16_bf16 v[2:17], v[110:113], v[114:117], v[2:17]
	s_mov_b32 m0, s1
	s_waitcnt lgkmcnt(0)
	ds_read_b128 v[102:105], v98 offset:16384
	ds_read_b128 v[106:109], v99
	ds_read_b128 v[110:113], v99 offset:4096
	ds_read_b128 v[114:117], v98 offset:20480
	v_mfma_f32_32x32x16_bf16 v[34:49], v[242:245], v[238:241], v[34:49]
	v_mfma_f32_32x32x16_bf16 v[18:33], v[246:249], v[238:241], v[18:33]
	v_mfma_f32_32x32x16_bf16 v[50:65], v[242:245], v[250:253], v[50:65]
	v_mfma_f32_32x32x16_bf16 v[2:17], v[246:249], v[250:253], v[2:17]
	s_waitcnt lgkmcnt(0)
	ds_read_b128 v[238:241], v100 offset:16384
	ds_read_b128 v[242:245], v101
	ds_read_b128 v[246:249], v101 offset:4096
	ds_read_b128 v[250:253], v100 offset:20480
	v_mfma_f32_32x32x16_bf16 v[34:49], v[106:109], v[102:105], v[34:49]
	v_mfma_f32_32x32x16_bf16 v[18:33], v[110:113], v[102:105], v[18:33]
	v_mfma_f32_32x32x16_bf16 v[50:65], v[106:109], v[114:117], v[50:65]
	v_mfma_f32_32x32x16_bf16 v[2:17], v[110:113], v[114:117], v[2:17]
	s_waitcnt vmcnt(0) lgkmcnt(0)
	s_barrier
; DI void gemm_out(const Params& p, char* lds) {
;     ...
;         for (int kt = 0; kt < 16; ++kt) {
;             if (kt + 1 < 16) OSTAGE((kt + 1) & 1, kt + 1);
;             const char* sb = lds + (kt & 1) * 28672; const char* sa = sb + 16384;
; #pragma unroll
;             for (int ks = 0; ks < 2; ++ks) {
;                 bf16x8 fw[4], fx[3];
; #pragma unroll
;                 for (int ct = 0; ct < 4; ++ct) fw[ct] = *(const bf16x8*)(sb + swz(wn * 64 + ct * 16 + q, 4 * ks + g));
; #pragma unroll
;                 for (int tt = 0; tt < 3; ++tt) fx[tt] = *(const bf16x8*)(sa + swz(wm * 48 + tt * 16 + q, 4 * ks + g));
; #pragma unroll
;                 for (int ct = 0; ct < 4; ++ct)
; #pragma unroll
;                     for (int tt = 0; tt < 3; ++tt) acc[ct][tt] = __builtin_amdgcn_mfma_f32_16x16x32_bf16(fw[ct], fx[tt], acc[ct][tt], 0, 0, 0);
;             }
;             __syncthreads();
;         }
	ds_read_b128 v[102:105], v74 offset:49152
	ds_read_b128 v[106:109], v96 offset:32768
	ds_read_b128 v[110:113], v96 offset:36864
	ds_read_b128 v[114:117], v74 offset:53248
	v_mfma_f32_32x32x16_bf16 v[34:49], v[242:245], v[238:241], v[34:49]
	v_mfma_f32_32x32x16_bf16 v[18:33], v[246:249], v[238:241], v[18:33]
	v_lshl_add_u64 v[254:255], v[76:77], 0, s[30:31]
	global_load_lds_dwordx4 v[254:255], off
	v_lshl_add_u64 v[254:255], v[78:79], 0, s[30:31]
	s_mov_b32 m0, s7
	s_nop 0
	global_load_lds_dwordx4 v[254:255], off
	v_lshl_add_u64 v[254:255], v[80:81], 0, s[30:31]
	s_mov_b32 m0, s38
	v_mfma_f32_32x32x16_bf16 v[50:65], v[242:245], v[250:253], v[50:65]
	global_load_lds_dwordx4 v[254:255], off
	v_lshl_add_u64 v[254:255], v[82:83], 0, s[30:31]
	s_mov_b32 m0, s39
	s_nop 0
	global_load_lds_dwordx4 v[254:255], off
	v_lshl_add_u64 v[254:255], v[84:85], 0, s[30:31]
	s_mov_b32 m0, s50
	v_mfma_f32_32x32x16_bf16 v[2:17], v[246:249], v[250:253], v[2:17]
	global_load_lds_dwordx4 v[254:255], off
	s_waitcnt lgkmcnt(0)
	ds_read_b128 v[238:241], v95 offset:49152
	ds_read_b128 v[242:245], v97 offset:32768
	ds_read_b128 v[246:249], v97 offset:36864
	ds_read_b128 v[250:253], v95 offset:53248
	v_mfma_f32_32x32x16_bf16 v[34:49], v[106:109], v[102:105], v[34:49]
	v_lshl_add_u64 v[254:255], v[86:87], 0, s[30:31]
	s_mov_b32 m0, s51
	s_nop 0
	global_load_lds_dwordx4 v[254:255], off
	v_mfma_f32_32x32x16_bf16 v[18:33], v[110:113], v[102:105], v[18:33]
	v_lshl_add_u64 v[254:255], v[88:89], 0, s[30:31]
	s_mov_b32 m0, s83
	s_nop 0
	global_load_lds_dwordx4 v[254:255], off
	v_mfma_f32_32x32x16_bf16 v[50:65], v[106:109], v[114:117], v[50:65]
	v_lshl_add_u64 v[254:255], v[90:91], 0, s[30:31]
	s_mov_b32 m0, s90
	s_nop 0
	global_load_lds_dwordx4 v[254:255], off
	v_mfma_f32_32x32x16_bf16 v[2:17], v[110:113], v[114:117], v[2:17]
	s_mov_b32 m0, s86
	s_waitcnt lgkmcnt(0)
	ds_read_b128 v[102:105], v98 offset:49152
	ds_read_b128 v[106:109], v99 offset:32768
	ds_read_b128 v[110:113], v99 offset:36864
	ds_read_b128 v[114:117], v98 offset:53248
	v_mfma_f32_32x32x16_bf16 v[34:49], v[242:245], v[238:241], v[34:49]
	v_mfma_f32_32x32x16_bf16 v[18:33], v[246:249], v[238:241], v[18:33]
	v_mfma_f32_32x32x16_bf16 v[50:65], v[242:245], v[250:253], v[50:65]
	v_mfma_f32_32x32x16_bf16 v[2:17], v[246:249], v[250:253], v[2:17]
	s_waitcnt lgkmcnt(0)
	ds_read_b128 v[238:241], v100 offset:49152
	ds_read_b128 v[242:245], v101 offset:32768
	ds_read_b128 v[246:249], v101 offset:36864
	ds_read_b128 v[250:253], v100 offset:53248
	v_mfma_f32_32x32x16_bf16 v[34:49], v[106:109], v[102:105], v[34:49]
	v_mfma_f32_32x32x16_bf16 v[18:33], v[110:113], v[102:105], v[18:33]
	v_mfma_f32_32x32x16_bf16 v[50:65], v[106:109], v[114:117], v[50:65]
	v_mfma_f32_32x32x16_bf16 v[2:17], v[110:113], v[114:117], v[2:17]
	s_waitcnt vmcnt(0) lgkmcnt(0)
	s_barrier
	ds_read_b128 v[102:105], v74 offset:16384
	ds_read_b128 v[106:109], v96
	ds_read_b128 v[110:113], v96 offset:4096
	ds_read_b128 v[114:117], v74 offset:20480
	v_mfma_f32_32x32x16_bf16 v[34:49], v[242:245], v[238:241], v[34:49]
	v_mfma_f32_32x32x16_bf16 v[18:33], v[246:249], v[238:241], v[18:33]
	v_lshl_add_u64 v[254:255], v[76:77], 0, s[36:37]
	global_load_lds_dwordx4 v[254:255], off
	v_lshl_add_u64 v[254:255], v[78:79], 0, s[36:37]
	s_mov_b32 m0, s87
	s_nop 0
	global_load_lds_dwordx4 v[254:255], off
	v_lshl_add_u64 v[254:255], v[80:81], 0, s[36:37]
	s_mov_b32 m0, s88
	v_mfma_f32_32x32x16_bf16 v[50:65], v[242:245], v[250:253], v[50:65]
	global_load_lds_dwordx4 v[254:255], off
	v_lshl_add_u64 v[254:255], v[82:83], 0, s[36:37]
	s_mov_b32 m0, s89
	s_nop 0
	global_load_lds_dwordx4 v[254:255], off
	v_lshl_add_u64 v[254:255], v[84:85], 0, s[36:37]
	s_mov_b32 m0, s91
	v_mfma_f32_32x32x16_bf16 v[2:17], v[246:249], v[250:253], v[2:17]
	global_load_lds_dwordx4 v[254:255], off
	s_waitcnt lgkmcnt(0)
	ds_read_b128 v[238:241], v95 offset:16384
	ds_read_b128 v[242:245], v97
	ds_read_b128 v[246:249], v97 offset:4096
	ds_read_b128 v[250:253], v95 offset:20480
	v_mfma_f32_32x32x16_bf16 v[34:49], v[106:109], v[102:105], v[34:49]
	v_lshl_add_u64 v[254:255], v[86:87], 0, s[36:37]
	s_mov_b32 m0, s92
	s_nop 0
	global_load_lds_dwordx4 v[254:255], off
	v_mfma_f32_32x32x16_bf16 v[18:33], v[110:113], v[102:105], v[18:33]
	v_lshl_add_u64 v[254:255], v[88:89], 0, s[36:37]
	s_mov_b32 m0, s93
	s_nop 0
	global_load_lds_dwordx4 v[254:255], off
	v_mfma_f32_32x32x16_bf16 v[50:65], v[106:109], v[114:117], v[50:65]
	v_lshl_add_u64 v[254:255], v[90:91], 0, s[36:37]
	s_mov_b32 m0, s94
	s_nop 0
	global_load_lds_dwordx4 v[254:255], off
	v_mfma_f32_32x32x16_bf16 v[2:17], v[110:113], v[114:117], v[2:17]
	s_mov_b32 m0, s1
	s_waitcnt lgkmcnt(0)
	ds_read_b128 v[102:105], v98 offset:16384
	ds_read_b128 v[106:109], v99
	ds_read_b128 v[110:113], v99 offset:4096
	ds_read_b128 v[114:117], v98 offset:20480
	v_mfma_f32_32x32x16_bf16 v[34:49], v[242:245], v[238:241], v[34:49]
	v_mfma_f32_32x32x16_bf16 v[18:33], v[246:249], v[238:241], v[18:33]
	v_mfma_f32_32x32x16_bf16 v[50:65], v[242:245], v[250:253], v[50:65]
	v_mfma_f32_32x32x16_bf16 v[2:17], v[246:249], v[250:253], v[2:17]
	s_waitcnt lgkmcnt(0)
	ds_read_b128 v[238:241], v100 offset:16384
	ds_read_b128 v[242:245], v101
	ds_read_b128 v[246:249], v101 offset:4096
	ds_read_b128 v[250:253], v100 offset:20480
	v_mfma_f32_32x32x16_bf16 v[34:49], v[106:109], v[102:105], v[34:49]
	v_mfma_f32_32x32x16_bf16 v[18:33], v[110:113], v[102:105], v[18:33]
	v_mfma_f32_32x32x16_bf16 v[50:65], v[106:109], v[114:117], v[50:65]
	v_mfma_f32_32x32x16_bf16 v[2:17], v[110:113], v[114:117], v[2:17]
	s_waitcnt vmcnt(0) lgkmcnt(0)
	s_barrier
; DI void gemm_out(const Params& p, char* lds) {
;     ...
;         const int mt = tile >> 3, nt = tile & 7; const int m0 = mt * 96, n0 = nt * 128;
;         f32x4 acc[4][3];
; #pragma unroll
;         for (int a = 0; a < 4; ++a)
; #pragma unroll
;             for (int b = 0; b < 3; ++b) acc[a][b] = (f32x4){0.f, 0.f, 0.f, 0.f};
;         unsigned soffb[4], soffa[3];
; #pragma unroll
;         for (int i = 0; i < 4; ++i) { const int row = 8 * (i * 4 + wave) + (lane >> 3); const int ch = (lane & 7) ^ ((row >> 1) & 7); soffb[i] = (unsigned)(row * 1024 + ch * 8); }
; #pragma unroll
;         for (int i = 0; i < 3; ++i) { const int row = 8 * (i * 4 + wave) + (lane >> 3); const int ch = (lane & 7) ^ ((row >> 1) & 7); soffa[i] = (unsigned)(row * 1024 + ch * 8); }
;         const u16* ga = A + (size_t)m0 * 1024; const u16* gb = B + (size_t)n0 * 1024;
;     ...
;         OSTAGE(0, 0);
;     ...
;         for (int kt = 0; kt < 16; ++kt) {
;             if (kt + 1 < 16) OSTAGE((kt + 1) & 1, kt + 1);
;             const char* sb = lds + (kt & 1) * 28672; const char* sa = sb + 16384;
; #pragma unroll
;             for (int ks = 0; ks < 2; ++ks) {
;                 bf16x8 fw[4], fx[3];
; #pragma unroll
;                 for (int ct = 0; ct < 4; ++ct) fw[ct] = *(const bf16x8*)(sb + swz(wn * 64 + ct * 16 + q, 4 * ks + g));
; #pragma unroll
;                 for (int tt = 0; tt < 3; ++tt) fx[tt] = *(const bf16x8*)(sa + swz(wm * 48 + tt * 16 + q, 4 * ks + g));
; #pragma unroll
;                 for (int ct = 0; ct < 4; ++ct)
; #pragma unroll
;                     for (int tt = 0; tt < 3; ++tt) acc[ct][tt] = __builtin_amdgcn_mfma_f32_16x16x32_bf16(fw[ct], fx[tt], acc[ct][tt], 0, 0, 0);
;             }
;             __syncthreads();
;         }
	ds_read_b128 v[102:105], v74 offset:49152
	ds_read_b128 v[106:109], v96 offset:32768
	ds_read_b128 v[110:113], v96 offset:36864
	ds_read_b128 v[114:117], v74 offset:53248
	v_mfma_f32_32x32x16_bf16 v[34:49], v[242:245], v[238:241], v[34:49]
	v_mfma_f32_32x32x16_bf16 v[18:33], v[246:249], v[238:241], v[18:33]
	v_lshl_add_u64 v[254:255], v[76:77], 0, s[68:69]
	global_load_lds_dwordx4 v[254:255], off
	v_lshl_add_u64 v[254:255], v[78:79], 0, s[68:69]
	s_mov_b32 m0, s7
	v_lshl_add_u64 v[76:77], v[76:77], 0, s[70:71]
	global_load_lds_dwordx4 v[254:255], off
	v_lshl_add_u64 v[254:255], v[80:81], 0, s[68:69]
	s_mov_b32 m0, s38
	v_mfma_f32_32x32x16_bf16 v[50:65], v[242:245], v[250:253], v[50:65]
	global_load_lds_dwordx4 v[254:255], off
	v_lshl_add_u64 v[254:255], v[82:83], 0, s[68:69]
	s_mov_b32 m0, s39
	s_nop 0
	global_load_lds_dwordx4 v[254:255], off
	v_lshl_add_u64 v[254:255], v[84:85], 0, s[68:69]
	s_mov_b32 m0, s50
	v_mfma_f32_32x32x16_bf16 v[2:17], v[246:249], v[250:253], v[2:17]
	global_load_lds_dwordx4 v[254:255], off
	s_waitcnt lgkmcnt(0)
	ds_read_b128 v[238:241], v95 offset:49152
	ds_read_b128 v[242:245], v97 offset:32768
	ds_read_b128 v[246:249], v97 offset:36864
	ds_read_b128 v[250:253], v95 offset:53248
	v_mfma_f32_32x32x16_bf16 v[34:49], v[106:109], v[102:105], v[34:49]
	v_lshl_add_u64 v[254:255], v[86:87], 0, s[68:69]
	s_mov_b32 m0, s51
	s_nop 0
	global_load_lds_dwordx4 v[254:255], off
	v_mfma_f32_32x32x16_bf16 v[18:33], v[110:113], v[102:105], v[18:33]
	v_lshl_add_u64 v[254:255], v[88:89], 0, s[68:69]
	s_mov_b32 m0, s83
	s_nop 0
	global_load_lds_dwordx4 v[254:255], off
	v_mfma_f32_32x32x16_bf16 v[50:65], v[106:109], v[114:117], v[50:65]
	v_lshl_add_u64 v[254:255], v[90:91], 0, s[68:69]
	s_mov_b32 m0, s90
	s_nop 0
	global_load_lds_dwordx4 v[254:255], off
	v_mfma_f32_32x32x16_bf16 v[2:17], v[110:113], v[114:117], v[2:17]
	s_mov_b32 m0, s86
	s_mov_b32 s86, 0
	s_waitcnt lgkmcnt(0)
	ds_read_b128 v[102:105], v98 offset:49152
	ds_read_b128 v[106:109], v99 offset:32768
	ds_read_b128 v[110:113], v99 offset:36864
	ds_read_b128 v[114:117], v98 offset:53248
	v_mfma_f32_32x32x16_bf16 v[34:49], v[242:245], v[238:241], v[34:49]
	v_mfma_f32_32x32x16_bf16 v[18:33], v[246:249], v[238:241], v[18:33]
	v_mfma_f32_32x32x16_bf16 v[50:65], v[242:245], v[250:253], v[50:65]
	v_mfma_f32_32x32x16_bf16 v[2:17], v[246:249], v[250:253], v[2:17]
	s_waitcnt lgkmcnt(0)
	ds_read_b128 v[238:241], v100 offset:49152
	ds_read_b128 v[242:245], v101 offset:32768
	ds_read_b128 v[246:249], v101 offset:36864
	ds_read_b128 v[250:253], v100 offset:53248
	v_mfma_f32_32x32x16_bf16 v[34:49], v[106:109], v[102:105], v[34:49]
	v_mfma_f32_32x32x16_bf16 v[18:33], v[110:113], v[102:105], v[18:33]
	v_mfma_f32_32x32x16_bf16 v[50:65], v[106:109], v[114:117], v[50:65]
	v_mfma_f32_32x32x16_bf16 v[2:17], v[110:113], v[114:117], v[2:17]
	s_waitcnt vmcnt(0) lgkmcnt(0)
	s_barrier
	global_load_lds_dwordx4 v[76:77], off
	v_lshl_add_u64 v[76:77], v[78:79], 0, s[70:71]
	s_mov_b32 m0, s87
	v_mfma_f32_32x32x16_bf16 v[34:49], v[242:245], v[238:241], v[34:49]
	global_load_lds_dwordx4 v[76:77], off
	v_lshl_add_u64 v[76:77], v[80:81], 0, s[70:71]
	s_mov_b32 m0, s88
	s_mov_b32 s88, 0
	global_load_lds_dwordx4 v[76:77], off
	v_lshl_add_u64 v[76:77], v[82:83], 0, s[70:71]
	s_mov_b32 m0, s89
	v_mfma_f32_32x32x16_bf16 v[18:33], v[246:249], v[238:241], v[18:33]
	global_load_lds_dwordx4 v[76:77], off
	v_lshl_add_u64 v[76:77], v[84:85], 0, s[70:71]
	s_mov_b32 m0, s91
	s_nop 0
	global_load_lds_dwordx4 v[76:77], off
	v_lshl_add_u64 v[76:77], v[86:87], 0, s[70:71]
	s_mov_b32 m0, s92
	v_mfma_f32_32x32x16_bf16 v[50:65], v[242:245], v[250:253], v[50:65]
	global_load_lds_dwordx4 v[76:77], off
	v_lshl_add_u64 v[76:77], v[88:89], 0, s[70:71]
	s_mov_b32 m0, s93
	s_nop 0
	global_load_lds_dwordx4 v[76:77], off
	v_lshl_add_u64 v[76:77], v[90:91], 0, s[70:71]
	s_mov_b32 m0, s94
	v_mfma_f32_32x32x16_bf16 v[2:17], v[246:249], v[250:253], v[2:17]
	global_load_lds_dwordx4 v[76:77], off
	ds_read_b128 v[76:79], v74 offset:16384
	ds_read_b128 v[80:83], v96
	ds_read_b128 v[84:87], v96 offset:4096
	ds_read_b128 v[88:91], v74 offset:20480
	s_waitcnt lgkmcnt(0)
	v_mfma_f32_32x32x16_bf16 v[34:49], v[80:83], v[76:79], v[34:49]
	v_mfma_f32_32x32x16_bf16 v[18:33], v[84:87], v[76:79], v[18:33]
	v_mfma_f32_32x32x16_bf16 v[50:65], v[80:83], v[88:91], v[50:65]
	v_mfma_f32_32x32x16_bf16 v[2:17], v[84:87], v[88:91], v[2:17]
	ds_read_b128 v[76:79], v95 offset:16384
	ds_read_b128 v[80:83], v97
	ds_read_b128 v[84:87], v97 offset:4096
	ds_read_b128 v[88:91], v95 offset:20480
	s_waitcnt lgkmcnt(0)
	v_mfma_f32_32x32x16_bf16 v[34:49], v[80:83], v[76:79], v[34:49]
	v_mfma_f32_32x32x16_bf16 v[18:33], v[84:87], v[76:79], v[18:33]
	v_mfma_f32_32x32x16_bf16 v[50:65], v[80:83], v[88:91], v[50:65]
	v_mfma_f32_32x32x16_bf16 v[2:17], v[84:87], v[88:91], v[2:17]
	ds_read_b128 v[76:79], v98 offset:16384
	ds_read_b128 v[80:83], v99
	ds_read_b128 v[84:87], v99 offset:4096
	ds_read_b128 v[88:91], v98 offset:20480
	s_waitcnt lgkmcnt(0)
	v_mfma_f32_32x32x16_bf16 v[34:49], v[80:83], v[76:79], v[34:49]
	v_mfma_f32_32x32x16_bf16 v[18:33], v[84:87], v[76:79], v[18:33]
	v_mfma_f32_32x32x16_bf16 v[50:65], v[80:83], v[88:91], v[50:65]
	v_mfma_f32_32x32x16_bf16 v[2:17], v[84:87], v[88:91], v[2:17]
	ds_read_b128 v[76:79], v100 offset:16384
	ds_read_b128 v[80:83], v101
	ds_read_b128 v[84:87], v101 offset:4096
	ds_read_b128 v[88:91], v100 offset:20480
	s_waitcnt vmcnt(0) lgkmcnt(0)
	s_barrier
	s_cbranch_scc1 .Lo_skipnext
	s_mov_b32 m0, s1
	s_lshr_b32 s86, s33, 3
	s_lshl_b32 s86, s86, 7
	s_and_b32 s88, s33, 7
	s_lshl_b32 s88, s88, 7
	s_ashr_i32 s87, s86, 31
	s_lshl_b64 s[92:93], s[86:87], 11
	s_add_u32 s92, s54, s92
	s_addc_u32 s93, s55, s93
	s_ashr_i32 s89, s88, 31
	s_lshl_b64 s[94:95], s[88:89], 11
	v_readlane_b32 s1, v236, 9
	s_add_u32 s94, s1, s94
	v_readlane_b32 s1, v236, 11
	s_addc_u32 s95, s1, s95
	v_lshl_add_u64 v[118:119], s[92:93], 0, v[66:67]
	global_load_lds_dwordx4 v[118:119], off
	v_lshl_add_u64 v[66:67], s[94:95], 0, v[66:67]
	s_mov_b32 m0, s7
	s_nop 0
	global_load_lds_dwordx4 v[66:67], off
	v_lshl_add_u64 v[66:67], s[92:93], 0, v[68:69]
	s_mov_b32 m0, s38
	s_nop 0
	global_load_lds_dwordx4 v[66:67], off
	v_lshl_add_u64 v[66:67], s[94:95], 0, v[68:69]
	s_mov_b32 m0, s39
	s_nop 0
	global_load_lds_dwordx4 v[66:67], off
	v_lshl_add_u64 v[66:67], s[92:93], 0, v[70:71]
	s_mov_b32 m0, s50
	s_nop 0
	global_load_lds_dwordx4 v[66:67], off
	v_lshl_add_u64 v[66:67], s[94:95], 0, v[70:71]
	s_mov_b32 m0, s51
	s_nop 0
	global_load_lds_dwordx4 v[66:67], off
	v_lshl_add_u64 v[66:67], s[92:93], 0, v[72:73]
	s_mov_b32 m0, s83
	s_nop 0
	global_load_lds_dwordx4 v[66:67], off
	v_lshl_add_u64 v[66:67], s[94:95], 0, v[72:73]
	s_mov_b32 m0, s90
	s_nop 0
	global_load_lds_dwordx4 v[66:67], off
